# p3 + leading half's pre-epilogue alignment barrier moved down past ~one MFMA block's worth of accumulator-independent epilogue head (row-scale / residual loads)
# baseline (speedup 1.0000x reference)
.LBB0_171:
.LBB0_173:
	ds_read_b128 v[152:155], v167
	v_add_u32_e32 v150, s0, v156
	s_cmp_gt_i32 s12, 7
	s_cselect_b64 s[0:1], -1, 0
	s_and_b64 s[2:3], s[6:7], s[0:1]
	s_waitcnt lgkmcnt(0)
	v_lshlrev_b32_e32 v0, 16, v152
	v_and_b32_e32 v151, 0xffff0000, v152
	v_add_f32_e32 v0, v0, v151
	v_lshlrev_b32_e32 v151, 16, v153
	v_and_b32_e32 v152, 0xffff0000, v153
	v_add_f32_e32 v151, v151, v152
	v_add_f32_e32 v0, v0, v151
	v_lshlrev_b32_e32 v151, 16, v154
	v_and_b32_e32 v152, 0xffff0000, v154
	v_add_f32_e32 v151, v151, v152
	v_lshlrev_b32_e32 v152, 16, v155
	v_and_b32_e32 v153, 0xffff0000, v155
	v_add_f32_e32 v152, v152, v153
	v_add_f32_e32 v151, v151, v152
	v_add_f32_e32 v0, v0, v151
	v_mov_b32_e32 v151, v0
	s_nop 1
	v_permlane16_swap_b32_e32 v0, v151
	v_add_f32_e32 v0, v0, v151
	ds_read_b128 v[152:155], v167 offset:1024
	v_mov_b32_e32 v151, v0
	s_nop 1
	v_permlane32_swap_b32_e32 v0, v151
	v_add_f32_e32 v0, v0, v151
	v_fmamk_f32 v0, v0, 0x3a000000, v240
	v_rsq_f32_e32 v0, v0
	s_waitcnt lgkmcnt(0)
	v_lshlrev_b32_e32 v151, 16, v152
	v_and_b32_e32 v152, 0xffff0000, v152
	v_add_f32_e32 v151, v151, v152
	v_lshlrev_b32_e32 v152, 16, v153
	v_and_b32_e32 v153, 0xffff0000, v153
	v_add_f32_e32 v152, v152, v153
	v_add_f32_e32 v151, v151, v152
	v_lshlrev_b32_e32 v152, 16, v154
	v_and_b32_e32 v153, 0xffff0000, v154
	v_add_f32_e32 v152, v152, v153
	v_lshlrev_b32_e32 v153, 16, v155
	v_and_b32_e32 v154, 0xffff0000, v155
	s_mov_b64 vcc, s[14:15]
	s_cbranch_vccz .Lalign_skip_0
	s_barrier
.Lalign_skip_0:
	v_pk_mul_f32 v[122:123], v[122:123], v[0:1] op_sel_hi:[1,0]
	v_add_f32_e32 v153, v153, v154
	v_mul_f32_e32 v178, 0x3d372713, v122
	v_add_f32_e32 v152, v152, v153
	v_mul_f32_e32 v177, 0x3fcc422a, v122
	v_fma_f32 v178, v122, v178, 1.0
	v_add_f32_e32 v151, v151, v152
	v_mul_f32_e32 v177, v177, v178
	v_mov_b32_e32 v152, v151
	v_mul_f32_e32 v177, 0xbfb8aa3b, v177
	s_nop 0
	v_permlane16_swap_b32_e32 v151, v152
	v_exp_f32_e32 v177, v177
	v_add_f32_e32 v175, v151, v152
	ds_read_b128 v[152:155], v167 offset:2048
	v_mul_f32_e32 v178, 0x3d372713, v123
	v_add_f32_e32 v177, 1.0, v177
	v_rcp_f32_e32 v177, v177
	v_fma_f32 v178, v123, v178, 1.0
	s_waitcnt lgkmcnt(0)
	v_lshlrev_b32_e32 v151, 16, v152
	v_and_b32_e32 v152, 0xffff0000, v152
	v_add_f32_e32 v151, v151, v152
	v_lshlrev_b32_e32 v152, 16, v153
	v_and_b32_e32 v153, 0xffff0000, v153
	v_add_f32_e32 v152, v152, v153
	v_add_f32_e32 v151, v151, v152
	v_lshlrev_b32_e32 v152, 16, v154
	v_and_b32_e32 v153, 0xffff0000, v154
	v_mul_f32_e32 v122, v122, v177
	v_mul_f32_e32 v177, 0x3fcc422a, v123
	v_add_f32_e32 v152, v152, v153
	v_lshlrev_b32_e32 v153, 16, v155
	v_and_b32_e32 v154, 0xffff0000, v155
	v_mul_f32_e32 v177, v177, v178
	v_add_f32_e32 v153, v153, v154
	v_mul_f32_e32 v177, 0xbfb8aa3b, v177
	v_add_f32_e32 v152, v152, v153
	v_exp_f32_e32 v177, v177
	v_add_f32_e32 v151, v151, v152
	v_mov_b32_e32 v152, v151
	s_nop 1
	v_permlane16_swap_b32_e32 v151, v152
	v_add_f32_e32 v173, v151, v152
	ds_read_b128 v[152:155], v167 offset:3072
	v_add_f32_e32 v177, 1.0, v177
	v_rcp_f32_e32 v177, v177
	v_pk_mul_f32 v[124:125], v[124:125], v[0:1] op_sel_hi:[1,0]
	v_pk_mul_f32 v[126:127], v[126:127], v[0:1] op_sel_hi:[1,0]
	v_mul_f32_e32 v178, 0x3d372713, v124
	s_waitcnt lgkmcnt(0)
	v_lshlrev_b32_e32 v151, 16, v152
	v_and_b32_e32 v152, 0xffff0000, v152
	v_mul_f32_e32 v123, v123, v177
	v_mul_f32_e32 v177, 0x3fcc422a, v124
	v_fma_f32 v178, v124, v178, 1.0
	v_add_f32_e32 v151, v151, v152
	v_lshlrev_b32_e32 v152, 16, v153
	v_and_b32_e32 v153, 0xffff0000, v153
	v_mul_f32_e32 v177, v177, v178
	v_add_f32_e32 v152, v152, v153
	v_mul_f32_e32 v177, 0xbfb8aa3b, v177
	v_add_f32_e32 v151, v151, v152
	v_lshlrev_b32_e32 v152, 16, v154
	v_and_b32_e32 v153, 0xffff0000, v154
	v_exp_f32_e32 v177, v177
	v_add_f32_e32 v152, v152, v153
	v_lshlrev_b32_e32 v153, 16, v155
	v_and_b32_e32 v154, 0xffff0000, v155
	v_add_f32_e32 v153, v153, v154
	v_add_f32_e32 v152, v152, v153
	v_add_f32_e32 v151, v151, v152
	v_add_f32_e32 v177, 1.0, v177
	v_mov_b32_e32 v152, v151
	v_rcp_f32_e32 v177, v177
	s_nop 0
	v_permlane16_swap_b32_e32 v151, v152
	v_add_f32_e32 v171, v151, v152
	ds_read_b128 v[152:155], v167 offset:8192
	v_mul_f32_e32 v178, 0x3d372713, v125
	v_mul_f32_e32 v124, v124, v177
	v_mul_f32_e32 v177, 0x3fcc422a, v125
	v_fma_f32 v178, v125, v178, 1.0
	v_mul_f32_e32 v177, v177, v178
	v_mul_f32_e32 v177, 0xbfb8aa3b, v177
	s_waitcnt lgkmcnt(0)
	v_lshlrev_b32_e32 v151, 16, v152
	v_and_b32_e32 v152, 0xffff0000, v152
	v_exp_f32_e32 v177, v177
	v_add_f32_e32 v151, v151, v152
	v_lshlrev_b32_e32 v152, 16, v153
	v_and_b32_e32 v153, 0xffff0000, v153
	v_add_f32_e32 v152, v152, v153
	v_add_f32_e32 v151, v151, v152
	v_lshlrev_b32_e32 v152, 16, v154
	v_and_b32_e32 v153, 0xffff0000, v154
	v_add_f32_e32 v152, v152, v153
	v_lshlrev_b32_e32 v153, 16, v155
	v_and_b32_e32 v154, 0xffff0000, v155
	v_add_f32_e32 v177, 1.0, v177
	v_add_f32_e32 v153, v153, v154
	v_rcp_f32_e32 v177, v177
	v_add_f32_e32 v152, v152, v153
	v_add_f32_e32 v151, v151, v152
	v_mov_b32_e32 v152, v151
	v_mul_f32_e32 v178, 0x3d372713, v126
	s_nop 0
	v_permlane16_swap_b32_e32 v151, v152
	v_mul_f32_e32 v125, v125, v177
	v_mul_f32_e32 v177, 0x3fcc422a, v126
	v_fma_f32 v178, v126, v178, 1.0
	v_add_f32_e32 v169, v151, v152
	ds_read_b128 v[152:155], v167 offset:9216
	v_mul_f32_e32 v177, v177, v178
	v_mul_f32_e32 v177, 0xbfb8aa3b, v177
	v_exp_f32_e32 v177, v177
	v_mul_f32_e32 v178, 0x3d372713, v127
	s_waitcnt lgkmcnt(0)
	v_lshlrev_b32_e32 v151, 16, v152
	v_and_b32_e32 v152, 0xffff0000, v152
	v_add_f32_e32 v151, v151, v152
	v_lshlrev_b32_e32 v152, 16, v153
	v_and_b32_e32 v153, 0xffff0000, v153
	v_add_f32_e32 v177, 1.0, v177
	v_add_f32_e32 v152, v152, v153
	v_rcp_f32_e32 v177, v177
	v_add_f32_e32 v151, v151, v152
	v_lshlrev_b32_e32 v152, 16, v154
	v_and_b32_e32 v153, 0xffff0000, v154
	v_add_f32_e32 v152, v152, v153
	v_lshlrev_b32_e32 v153, 16, v155
	v_and_b32_e32 v154, 0xffff0000, v155
	v_add_f32_e32 v153, v153, v154
	v_add_f32_e32 v152, v152, v153
	v_mul_f32_e32 v126, v126, v177
	v_mul_f32_e32 v177, 0x3fcc422a, v127
	v_fma_f32 v178, v127, v178, 1.0
	v_add_f32_e32 v151, v151, v152
	v_mul_f32_e32 v177, v177, v178
	v_mov_b32_e32 v152, v151
	v_mul_f32_e32 v177, 0xbfb8aa3b, v177
	s_nop 0
	v_permlane16_swap_b32_e32 v151, v152
	v_exp_f32_e32 v177, v177
	v_add_f32_e32 v161, v151, v152
	ds_read_b128 v[152:155], v167 offset:10240
	v_pk_mul_f32 v[128:129], v[128:129], v[0:1] op_sel_hi:[1,0]
	v_add_f32_e32 v177, 1.0, v177
	v_rcp_f32_e32 v177, v177
	v_mul_f32_e32 v178, 0x3d372713, v128
	s_waitcnt lgkmcnt(0)
	v_lshlrev_b32_e32 v151, 16, v152
	v_and_b32_e32 v152, 0xffff0000, v152
	v_add_f32_e32 v151, v151, v152
	v_lshlrev_b32_e32 v152, 16, v153
	v_and_b32_e32 v153, 0xffff0000, v153
	v_add_f32_e32 v152, v152, v153
	v_add_f32_e32 v151, v151, v152
	v_lshlrev_b32_e32 v152, 16, v154
	v_and_b32_e32 v153, 0xffff0000, v154
	v_mul_f32_e32 v127, v127, v177
	v_mul_f32_e32 v177, 0x3fcc422a, v128
	v_fma_f32 v178, v128, v178, 1.0
	v_add_f32_e32 v152, v152, v153
	v_lshlrev_b32_e32 v153, 16, v155
	v_and_b32_e32 v154, 0xffff0000, v155
	v_mul_f32_e32 v177, v177, v178
	v_add_f32_e32 v153, v153, v154
	v_mul_f32_e32 v177, 0xbfb8aa3b, v177
	v_add_f32_e32 v152, v152, v153
	v_exp_f32_e32 v177, v177
	v_add_f32_e32 v151, v151, v152
	v_mov_b32_e32 v152, v151
	s_nop 1
	v_permlane16_swap_b32_e32 v151, v152
	v_add_f32_e32 v159, v151, v152
	ds_read_b128 v[152:155], v167 offset:11264
	v_add_f32_e32 v177, 1.0, v177
	v_rcp_f32_e32 v177, v177
	v_mul_f32_e32 v178, 0x3d372713, v129
	v_fma_f32 v178, v129, v178, 1.0
	s_waitcnt lgkmcnt(0)
	v_lshlrev_b32_e32 v151, 16, v152
	v_and_b32_e32 v152, 0xffff0000, v152
	v_mul_f32_e32 v128, v128, v177
	v_mul_f32_e32 v177, 0x3fcc422a, v129
	v_add_f32_e32 v151, v151, v152
	v_lshlrev_b32_e32 v152, 16, v153
	v_and_b32_e32 v153, 0xffff0000, v153
	v_mul_f32_e32 v177, v177, v178
	v_add_f32_e32 v152, v152, v153
	v_mul_f32_e32 v177, 0xbfb8aa3b, v177
	v_add_f32_e32 v151, v151, v152
	v_lshlrev_b32_e32 v152, 16, v154
	v_and_b32_e32 v153, 0xffff0000, v154
	v_exp_f32_e32 v177, v177
	v_add_f32_e32 v152, v152, v153
	v_lshlrev_b32_e32 v153, 16, v155
	v_and_b32_e32 v154, 0xffff0000, v155
	v_add_f32_e32 v153, v153, v154
	v_add_f32_e32 v152, v152, v153
	v_add_f32_e32 v151, v151, v152
	v_add_f32_e32 v177, 1.0, v177
	v_mov_b32_e32 v152, v151
	v_rcp_f32_e32 v177, v177
	s_nop 0
	v_permlane16_swap_b32_e32 v151, v152
	v_add_f32_e32 v157, v151, v152
	v_lshl_or_b32 v152, s12, 8, v165
	v_ashrrev_i32_e32 v153, 31, v152
	v_ashrrev_i32_e32 v151, 31, v150
	v_lshl_add_u64 v[152:153], v[152:153], 1, v[140:141]
	v_lshlrev_b64 v[154:155], 13, v[150:151]
	v_mul_f32_e32 v129, v129, v177
	v_mul_f32_e32 v177, v123, v123
	v_lshl_add_u64 v[154:155], v[152:153], 0, v[154:155]
	v_fmac_f32_e32 v177, v122, v122
	v_mul_f32_e32 v178, v125, v125
	v_cvt_pk_bf16_f32 v122, v122, v123
	v_pk_mul_f32 v[114:115], v[114:115], v[0:1] op_sel_hi:[1,0]
	v_fmac_f32_e32 v178, v124, v124
	v_cvt_pk_bf16_f32 v123, v124, v125
	v_cvt_pk_bf16_f32 v124, v126, v127
	v_cvt_pk_bf16_f32 v125, v128, v129
	global_store_dwordx4 v[154:155], v[122:125], off
	v_pk_mul_f32 v[116:117], v[116:117], v[0:1] op_sel_hi:[1,0]
	v_pk_mul_f32 v[120:121], v[120:121], v[0:1] op_sel_hi:[1,0]
	v_mul_f32_e32 v122, 0x3d372713, v114
	v_pk_mul_f32 v[118:119], v[118:119], v[0:1] op_sel_hi:[1,0]
	v_mul_f32_e32 v0, 0x3fcc422a, v114
	v_fma_f32 v122, v114, v122, 1.0
	v_mul_f32_e32 v0, v0, v122
	v_mul_f32_e32 v0, 0xbfb8aa3b, v0
	v_exp_f32_e32 v0, v0
	v_mul_f32_e32 v122, 0x3d372713, v115
	v_fma_f32 v122, v115, v122, 1.0
	v_add_f32_e32 v177, v177, v178
	v_add_f32_e32 v0, 1.0, v0
	v_rcp_f32_e32 v0, v0
	v_mul_f32_e32 v178, v127, v127
	v_mul_f32_e32 v179, v129, v129
	v_fmac_f32_e32 v178, v126, v126
	v_mul_f32_e32 v0, v114, v0
	v_mul_f32_e32 v114, 0x3fcc422a, v115
	v_mul_f32_e32 v114, v114, v122
	v_mul_f32_e32 v114, 0xbfb8aa3b, v114
	v_exp_f32_e32 v114, v114
	v_mul_f32_e32 v122, 0x3d372713, v116
	v_fma_f32 v122, v116, v122, 1.0
	v_fmac_f32_e32 v179, v128, v128
	v_add_f32_e32 v114, 1.0, v114
	v_rcp_f32_e32 v114, v114
	v_add_f32_e32 v178, v178, v179
	v_add_f32_e32 v177, v177, v178
	v_mov_b32_e32 v176, v175
	v_mul_f32_e32 v114, v115, v114
	v_mul_f32_e32 v115, 0x3fcc422a, v116
	v_mul_f32_e32 v115, v115, v122
	v_mul_f32_e32 v115, 0xbfb8aa3b, v115
	v_exp_f32_e32 v115, v115
	v_mul_f32_e32 v122, 0x3d372713, v117
	v_fma_f32 v122, v117, v122, 1.0
	v_mov_b32_e32 v174, v173
	v_add_f32_e32 v115, 1.0, v115
	v_rcp_f32_e32 v115, v115
	v_mov_b32_e32 v172, v171
	v_mov_b32_e32 v170, v169
	v_mov_b32_e32 v168, v161
	v_mul_f32_e32 v115, v116, v115
	v_mul_f32_e32 v116, 0x3fcc422a, v117
	v_mul_f32_e32 v116, v116, v122
	v_mul_f32_e32 v116, 0xbfb8aa3b, v116
	v_exp_f32_e32 v116, v116
	v_mul_f32_e32 v122, 0x3d372713, v118
	v_fma_f32 v122, v118, v122, 1.0
	v_mov_b32_e32 v160, v159
	v_add_f32_e32 v116, 1.0, v116
	v_rcp_f32_e32 v116, v116
	v_mov_b32_e32 v158, v157
	v_permlane32_swap_b32_e32 v175, v176
	v_mul_f32_e32 v116, v117, v116
	v_mul_f32_e32 v117, 0x3fcc422a, v118
	v_mul_f32_e32 v117, v117, v122
	v_mul_f32_e32 v117, 0xbfb8aa3b, v117
	v_exp_f32_e32 v117, v117
	v_mul_f32_e32 v122, 0x3d372713, v119
	v_fma_f32 v122, v119, v122, 1.0
	v_permlane32_swap_b32_e32 v173, v174
	v_add_f32_e32 v117, 1.0, v117
	v_rcp_f32_e32 v117, v117
	v_permlane32_swap_b32_e32 v171, v172
	v_permlane32_swap_b32_e32 v169, v170
	v_mul_f32_e32 v117, v118, v117
	v_mul_f32_e32 v118, 0x3fcc422a, v119
	v_mul_f32_e32 v118, v118, v122
	v_mul_f32_e32 v118, 0xbfb8aa3b, v118
	v_exp_f32_e32 v118, v118
	v_mul_f32_e32 v122, 0x3d372713, v120
	v_fma_f32 v122, v120, v122, 1.0
	v_permlane32_swap_b32_e32 v161, v168
	v_add_f32_e32 v118, 1.0, v118
	v_rcp_f32_e32 v118, v118
	v_permlane32_swap_b32_e32 v159, v160
	v_permlane32_swap_b32_e32 v157, v158
	v_mul_f32_e32 v118, v119, v118
	v_mul_f32_e32 v119, 0x3fcc422a, v120
	v_mul_f32_e32 v119, v119, v122
	v_mul_f32_e32 v119, 0xbfb8aa3b, v119
	v_exp_f32_e32 v119, v119
	v_mul_f32_e32 v122, 0x3d372713, v121
	v_fma_f32 v122, v121, v122, 1.0
	v_add_f32_e32 v119, 1.0, v119
	v_rcp_f32_e32 v119, v119
	s_nop 0
	v_mul_f32_e32 v119, v120, v119
	v_mul_f32_e32 v120, 0x3fcc422a, v121
	v_mul_f32_e32 v120, v120, v122
	v_mul_f32_e32 v120, 0xbfb8aa3b, v120
	v_exp_f32_e32 v120, v120
	v_mul_f32_e32 v122, v116, v116
	v_fmac_f32_e32 v122, v115, v115
	v_add_f32_e32 v120, 1.0, v120
	v_rcp_f32_e32 v120, v120
	s_nop 0
	v_mul_f32_e32 v120, v121, v120
	v_mul_f32_e32 v121, v114, v114
	v_fmac_f32_e32 v121, v0, v0
	v_add_f32_e32 v121, v121, v122
	v_mul_f32_e32 v122, v118, v118
	v_mul_f32_e32 v123, v120, v120
	v_fmac_f32_e32 v122, v117, v117
	v_fmac_f32_e32 v123, v119, v119
	v_add_f32_e32 v122, v122, v123
	v_add_f32_e32 v121, v121, v122
	v_add_f32_e32 v121, v177, v121
	v_cvt_pk_bf16_f32 v114, v0, v114
	v_mov_b32_e32 v0, v121
	s_nop 1
	v_permlane16_swap_b32_e32 v121, v0
	v_add_f32_e32 v0, v121, v0
	v_cvt_pk_bf16_f32 v115, v115, v116
	v_cvt_pk_bf16_f32 v116, v117, v118
	v_cvt_pk_bf16_f32 v117, v119, v120
	global_store_dwordx4 v[154:155], v[114:117], off offset:256
	s_nop 1
	v_mov_b32_e32 v114, v0
	s_nop 1
	v_permlane32_swap_b32_e32 v0, v114
	s_and_saveexec_b64 s[0:1], s[2:3]
	s_cbranch_execz .LBB0_175
	v_add_f32_e32 v0, v0, v114
	v_lshlrev_b64 v[114:115], 7, v[150:151]
	s_lshl_b32 s36, s12, 2
	v_lshl_add_u64 v[114:115], v[138:139], 0, v[114:115]
	s_mov_b32 s37, s40
	v_lshl_add_u64 v[114:115], s[36:37], 2, v[114:115]
	s_lshl_b32 s36, s28, 2
	v_lshl_add_u64 v[114:115], v[114:115], 0, s[36:37]
	global_store_dword v[114:115], v0, off offset:-128

.LBB0_423:
	v_lshl_or_b32 v216, s14, 8, v250
	v_lshl_add_u32 v232, s16, 8, v238
	v_ashrrev_i32_e32 v217, 31, v216
	v_lshlrev_b64 v[234:235], 1, v[216:217]
	v_ashrrev_i32_e32 v233, 31, v232
	v_lshl_add_u64 v[134:135], v[202:203], 0, v[234:235]
	v_lshlrev_b64 v[236:237], 12, v[232:233]
	v_lshl_add_u64 v[130:131], v[134:135], 0, v[236:237]
	global_load_dwordx4 v[190:193], v[130:131], off
	global_load_dwordx4 v[186:189], v[130:131], off offset:256
	v_or_b32_e32 v230, 16, v232
	v_ashrrev_i32_e32 v231, 31, v230
	v_lshlrev_b64 v[130:131], 12, v[230:231]
	v_or_b32_e32 v228, 32, v232
	v_lshl_add_u64 v[130:131], v[134:135], 0, v[130:131]
	v_ashrrev_i32_e32 v229, 31, v228
	global_load_dwordx4 v[182:185], v[130:131], off
	global_load_dwordx4 v[178:181], v[130:131], off offset:256
	v_lshlrev_b64 v[130:131], 12, v[228:229]
	v_or_b32_e32 v226, 48, v232
	v_lshl_add_u64 v[130:131], v[134:135], 0, v[130:131]
	v_ashrrev_i32_e32 v227, 31, v226
	global_load_dwordx4 v[174:177], v[130:131], off
	global_load_dwordx4 v[170:173], v[130:131], off offset:256
	v_lshlrev_b64 v[130:131], 12, v[226:227]
	v_add_u32_e32 v224, 0x80, v232
	v_lshl_add_u64 v[130:131], v[134:135], 0, v[130:131]
	v_ashrrev_i32_e32 v225, 31, v224
	global_load_dwordx4 v[166:169], v[130:131], off
	global_load_dwordx4 v[162:165], v[130:131], off offset:256
	v_lshlrev_b64 v[130:131], 12, v[224:225]
	v_add_u32_e32 v222, 0x90, v232
	v_lshl_add_u64 v[130:131], v[134:135], 0, v[130:131]
	v_ashrrev_i32_e32 v223, 31, v222
	global_load_dwordx4 v[158:161], v[130:131], off
	global_load_dwordx4 v[154:157], v[130:131], off offset:256
	v_lshlrev_b64 v[130:131], 12, v[222:223]
	v_add_u32_e32 v220, 0xa0, v232
	v_add_u32_e32 v218, 0xb0, v232
	v_lshl_add_u64 v[130:131], v[134:135], 0, v[130:131]
	v_ashrrev_i32_e32 v221, 31, v220
	v_ashrrev_i32_e32 v219, 31, v218
	global_load_dwordx4 v[150:153], v[130:131], off
	global_load_dwordx4 v[146:149], v[130:131], off offset:256
	v_lshlrev_b64 v[130:131], 12, v[220:221]
	v_lshlrev_b64 v[136:137], 12, v[218:219]
	v_lshl_add_u64 v[130:131], v[134:135], 0, v[130:131]
	v_lshl_add_u64 v[134:135], v[134:135], 0, v[136:137]
	global_load_dwordx4 v[138:141], v[130:131], off
	s_nop 0
	global_load_dwordx4 v[130:133], v[130:131], off offset:256
	s_nop 0
	global_load_dwordx4 v[142:145], v[134:135], off
	s_nop 0
	global_load_dwordx4 v[134:137], v[134:135], off offset:256
	s_mov_b64 vcc, s[2:3]
	s_cbranch_vccz .Lalign_skip_3
	s_barrier
.Lalign_skip_3:
	s_lshl_b32 s14, s14, 2
	s_ashr_i32 s15, s14, 31
	s_waitcnt vmcnt(0)
	v_lshlrev_b32_e32 v206, 16, v190
	v_and_b32_e32 v207, 0xffff0000, v190
	v_lshlrev_b32_e32 v190, 16, v191
	v_and_b32_e32 v191, 0xffff0000, v191
	v_pk_add_f32 v[124:125], v[124:125], v[190:191]
	v_pk_add_f32 v[122:123], v[122:123], v[206:207]
	v_lshlrev_b32_e32 v252, 16, v192
	v_and_b32_e32 v253, 0xffff0000, v192
	v_mul_f32_e32 v0, v123, v123
	v_mul_f32_e32 v190, v125, v125
	v_pk_add_f32 v[126:127], v[126:127], v[252:253]
	v_fmac_f32_e32 v0, v122, v122
	v_fmac_f32_e32 v190, v124, v124
	v_add_f32_e32 v0, v0, v190
	v_mul_f32_e32 v190, v127, v127
	v_lshlrev_b32_e32 v192, 16, v193
	v_and_b32_e32 v193, 0xffff0000, v193
	v_fmac_f32_e32 v190, v126, v126
	v_cvt_pk_bf16_f32 v122, v122, v123
	v_cvt_pk_bf16_f32 v123, v124, v125
	v_cvt_pk_bf16_f32 v124, v126, v127
	v_lshl_add_u64 v[126:127], v[202:203], 0, v[236:237]
	v_pk_add_f32 v[128:129], v[128:129], v[192:193]
	v_lshl_add_u64 v[126:127], v[126:127], 0, v[234:235]
	v_cvt_pk_bf16_f32 v125, v128, v129
	v_mul_f32_e32 v191, v129, v129
	global_store_dwordx4 v[126:127], v[122:125], off
	v_fmac_f32_e32 v191, v128, v128
	v_lshlrev_b32_e32 v128, 16, v188
	v_lshlrev_b32_e32 v122, 16, v186
	v_and_b32_e32 v123, 0xffff0000, v186
	v_lshlrev_b32_e32 v124, 16, v187
	v_and_b32_e32 v125, 0xffff0000, v187
	v_and_b32_e32 v129, 0xffff0000, v188
	v_lshlrev_b32_e32 v186, 16, v189
	v_and_b32_e32 v187, 0xffff0000, v189
	v_pk_add_f32 v[120:121], v[120:121], v[124:125]
	v_pk_add_f32 v[118:119], v[118:119], v[122:123]
	v_pk_add_f32 v[122:123], v[116:117], v[186:187]
	v_pk_add_f32 v[116:117], v[114:115], v[128:129]
	v_mul_f32_e32 v114, v119, v119
	v_mul_f32_e32 v115, v121, v121
	v_fmac_f32_e32 v114, v118, v118
	v_fmac_f32_e32 v115, v120, v120
	v_add_f32_e32 v114, v114, v115
	v_mul_f32_e32 v115, v117, v117
	v_mul_f32_e32 v124, v123, v123
	v_fmac_f32_e32 v115, v116, v116
	v_fmac_f32_e32 v124, v122, v122
	v_add_f32_e32 v190, v190, v191
	v_add_f32_e32 v115, v115, v124
	v_add_f32_e32 v0, v0, v190
	v_add_f32_e32 v114, v114, v115
	v_add_f32_e32 v0, v0, v114
	v_cvt_pk_bf16_f32 v114, v118, v119
	v_cvt_pk_bf16_f32 v115, v120, v121
	v_cvt_pk_bf16_f32 v116, v116, v117
	v_cvt_pk_bf16_f32 v117, v122, v123
	global_store_dwordx4 v[126:127], v[114:117], off offset:256
	s_nop 1
	v_mov_b32_e32 v114, v0
	s_nop 1
	v_permlane16_swap_b32_e32 v0, v114
	v_add_f32_e32 v0, v0, v114
	v_mov_b32_e32 v114, v0
	s_nop 1
	v_permlane32_swap_b32_e32 v0, v114
	s_and_saveexec_b64 s[16:17], s[6:7]
	s_cbranch_execz .LBB0_425
	v_lshlrev_b64 v[116:117], 6, v[232:233]
	v_lshl_add_u64 v[116:117], v[204:205], 0, v[116:117]
	v_lshl_add_u64 v[116:117], s[14:15], 1, v[116:117]
	s_lshl_b32 s18, s29, 1
	s_mov_b32 s19, s40
	v_lshl_add_u64 v[116:117], v[116:117], 0, s[18:19]
	v_add_f32_e32 v0, v0, v114
	v_cvt_pk_bf16_f32 v0, v0, v1
	global_store_short v[116:117], v0, off

.LBB0_508:
.LBB0_510:
	ds_read_b128 v[158:161], v167
	ds_read_b128 v[168:171], v167 offset:1024
	s_mul_hi_i32 s8, s2, 0x2aaaaaab
	s_lshr_b32 s9, s8, 31
	s_ashr_i32 s8, s8, 1
	s_add_i32 s15, s8, s9
	v_mov_b32_e32 v0, 0xf000000
	v_mad_i64_i32 v[152:153], s[8:9], s15, v0, v[140:141]
	s_waitcnt lgkmcnt(0)
	v_lshlrev_b32_e32 v0, 16, v158
	v_and_b32_e32 v150, 0xffff0000, v158
	v_add_f32_e32 v0, v0, v150
	v_lshlrev_b32_e32 v150, 16, v159
	v_and_b32_e32 v151, 0xffff0000, v159
	v_add_f32_e32 v150, v150, v151
	v_add_f32_e32 v0, v0, v150
	v_lshlrev_b32_e32 v150, 16, v160
	v_and_b32_e32 v151, 0xffff0000, v160
	v_add_f32_e32 v150, v150, v151
	v_lshlrev_b32_e32 v151, 16, v161
	v_and_b32_e32 v154, 0xffff0000, v161
	v_add_f32_e32 v151, v151, v154
	v_add_f32_e32 v150, v150, v151
	v_add_f32_e32 v0, v0, v150
	v_mov_b32_e32 v150, v0
	s_nop 1
	v_permlane16_swap_b32_e32 v0, v150
	v_add_f32_e32 v0, v0, v150
	v_mov_b32_e32 v150, v0
	s_nop 1
	v_permlane32_swap_b32_e32 v0, v150
	v_add_f32_e32 v0, v0, v150
	v_lshlrev_b32_e32 v150, 16, v168
	v_and_b32_e32 v151, 0xffff0000, v168
	v_add_f32_e32 v150, v150, v151
	v_lshlrev_b32_e32 v151, 16, v169
	v_and_b32_e32 v154, 0xffff0000, v169
	v_add_f32_e32 v151, v151, v154
	v_add_f32_e32 v150, v150, v151
	v_lshlrev_b32_e32 v151, 16, v170
	v_and_b32_e32 v154, 0xffff0000, v170
	v_add_f32_e32 v151, v151, v154
	v_lshlrev_b32_e32 v154, 16, v171
	v_and_b32_e32 v155, 0xffff0000, v171
	v_add_f32_e32 v154, v154, v155
	ds_read_b128 v[158:161], v167 offset:2048
	ds_read_b128 v[176:179], v167 offset:3072
	v_add_f32_e32 v151, v151, v154
	v_add_f32_e32 v150, v150, v151
	v_mov_b32_e32 v151, v150
	s_nop 1
	v_permlane16_swap_b32_e32 v150, v151
	v_add_f32_e32 v173, v150, v151
	s_waitcnt lgkmcnt(0)
	v_lshlrev_b32_e32 v150, 16, v158
	v_and_b32_e32 v151, 0xffff0000, v158
	v_add_f32_e32 v150, v150, v151
	v_lshlrev_b32_e32 v151, 16, v159
	v_and_b32_e32 v154, 0xffff0000, v159
	v_add_f32_e32 v151, v151, v154
	v_add_f32_e32 v150, v150, v151
	v_lshlrev_b32_e32 v151, 16, v160
	v_and_b32_e32 v154, 0xffff0000, v160
	v_add_f32_e32 v151, v151, v154
	v_lshlrev_b32_e32 v154, 16, v161
	v_and_b32_e32 v155, 0xffff0000, v161
	v_add_f32_e32 v154, v154, v155
	v_add_f32_e32 v151, v151, v154
	v_add_f32_e32 v150, v150, v151
	v_mov_b32_e32 v151, v150
	s_nop 1
	v_permlane16_swap_b32_e32 v150, v151
	v_add_f32_e32 v171, v150, v151
	v_lshlrev_b32_e32 v150, 16, v176
	v_and_b32_e32 v151, 0xffff0000, v176
	v_add_f32_e32 v150, v150, v151
	v_lshlrev_b32_e32 v151, 16, v177
	v_and_b32_e32 v154, 0xffff0000, v177
	v_add_f32_e32 v151, v151, v154
	v_add_f32_e32 v150, v150, v151
	v_lshlrev_b32_e32 v151, 16, v178
	v_and_b32_e32 v154, 0xffff0000, v178
	v_add_f32_e32 v151, v151, v154
	v_lshlrev_b32_e32 v154, 16, v179
	v_and_b32_e32 v155, 0xffff0000, v179
	v_add_f32_e32 v154, v154, v155
	ds_read_b128 v[158:161], v167 offset:8192
	ds_read_b128 v[176:179], v167 offset:9216
	v_add_f32_e32 v151, v151, v154
	v_add_f32_e32 v150, v150, v151
	v_mov_b32_e32 v151, v150
	s_nop 1
	v_permlane16_swap_b32_e32 v150, v151
	v_add_f32_e32 v169, v150, v151
	s_waitcnt lgkmcnt(0)
	v_lshlrev_b32_e32 v150, 16, v158
	v_and_b32_e32 v151, 0xffff0000, v158
	v_add_f32_e32 v150, v150, v151
	v_lshlrev_b32_e32 v151, 16, v159
	v_and_b32_e32 v154, 0xffff0000, v159
	v_add_f32_e32 v151, v151, v154
	v_add_f32_e32 v150, v150, v151
	v_lshlrev_b32_e32 v151, 16, v160
	v_and_b32_e32 v154, 0xffff0000, v160
	v_add_f32_e32 v151, v151, v154
	v_lshlrev_b32_e32 v154, 16, v161
	v_and_b32_e32 v155, 0xffff0000, v161
	v_add_f32_e32 v154, v154, v155
	v_add_f32_e32 v151, v151, v154
	v_add_f32_e32 v150, v150, v151
	s_mov_b64 vcc, s[10:11]
	s_cbranch_vccz .Lalign_skip_1
	s_barrier
.Lalign_skip_1:
	v_mov_b32_e32 v151, v150
	s_nop 1
	v_permlane16_swap_b32_e32 v150, v151
	v_add_f32_e32 v161, v150, v151
	v_lshlrev_b32_e32 v150, 16, v176
	v_and_b32_e32 v151, 0xffff0000, v176
	v_add_f32_e32 v150, v150, v151
	v_lshlrev_b32_e32 v151, 16, v177
	v_and_b32_e32 v154, 0xffff0000, v177
	v_add_f32_e32 v151, v151, v154
	v_add_f32_e32 v150, v150, v151
	v_lshlrev_b32_e32 v151, 16, v178
	v_and_b32_e32 v154, 0xffff0000, v178
	v_add_f32_e32 v151, v151, v154
	v_lshlrev_b32_e32 v154, 16, v179
	v_and_b32_e32 v155, 0xffff0000, v179
	v_add_f32_e32 v154, v154, v155
	ds_read_b128 v[176:179], v167 offset:10240
	ds_read_b128 v[180:183], v167 offset:11264
	v_add_f32_e32 v151, v151, v154
	v_add_f32_e32 v150, v150, v151
	v_mov_b32_e32 v151, v150
	s_nop 1
	v_permlane16_swap_b32_e32 v150, v151
	v_add_f32_e32 v159, v150, v151
	s_waitcnt lgkmcnt(0)
	v_lshlrev_b32_e32 v150, 16, v176
	v_and_b32_e32 v151, 0xffff0000, v176
	v_add_f32_e32 v150, v150, v151
	v_lshlrev_b32_e32 v151, 16, v177
	v_and_b32_e32 v154, 0xffff0000, v177
	v_add_f32_e32 v151, v151, v154
	v_add_f32_e32 v150, v150, v151
	v_lshlrev_b32_e32 v151, 16, v178
	v_and_b32_e32 v154, 0xffff0000, v178
	v_add_f32_e32 v151, v151, v154
	v_lshlrev_b32_e32 v154, 16, v179
	v_and_b32_e32 v155, 0xffff0000, v179
	v_add_f32_e32 v154, v154, v155
	v_add_f32_e32 v151, v151, v154
	v_add_f32_e32 v150, v150, v151
	v_mov_b32_e32 v151, v150
	s_nop 1
	v_permlane16_swap_b32_e32 v150, v151
	v_add_f32_e32 v157, v150, v151
	v_lshlrev_b32_e32 v150, 16, v180
	v_and_b32_e32 v151, 0xffff0000, v180
	v_add_f32_e32 v150, v150, v151
	v_lshlrev_b32_e32 v151, 16, v181
	v_and_b32_e32 v154, 0xffff0000, v181
	v_add_f32_e32 v151, v151, v154
	v_add_f32_e32 v150, v150, v151
	v_lshlrev_b32_e32 v151, 16, v182
	v_and_b32_e32 v154, 0xffff0000, v182
	v_add_f32_e32 v151, v151, v154
	v_lshlrev_b32_e32 v154, 16, v183
	v_and_b32_e32 v155, 0xffff0000, v183
	v_add_f32_e32 v154, v154, v155
	s_lshl_b32 s13, s2, 8
	s_mul_i32 s8, s15, 0xfffff400
	v_add_f32_e32 v151, v151, v154
	s_add_i32 s8, s8, s13
	v_add_f32_e32 v150, v150, v151
	v_fmamk_f32 v0, v0, 0x3a000000, v240
	v_mov_b32_e32 v151, v150
	v_or_b32_e32 v176, s8, v165
	v_rsq_f32_e32 v0, v0
	v_permlane16_swap_b32_e32 v150, v151
	v_ashrrev_i32_e32 v177, 31, v176
	v_add_f32_e32 v154, v150, v151
	v_add_u32_e32 v150, s3, v156
	v_lshl_add_u64 v[152:153], v[176:177], 1, v[152:153]
	s_movk_i32 s3, 0x1800
	v_mad_i64_i32 v[180:181], s[8:9], v150, s3, v[152:153]
	s_and_b32 s3, s2, -4
	v_mov_b32_e32 v174, v173
	v_mov_b32_e32 v172, v171
	v_mov_b32_e32 v170, v169
	v_mov_b32_e32 v168, v161
	v_mov_b32_e32 v160, v159
	v_mov_b32_e32 v158, v157
	v_mov_b32_e32 v155, v154
	s_cmp_eq_u32 s3, 4
	v_permlane32_swap_b32_e32 v173, v174
	v_permlane32_swap_b32_e32 v171, v172
	v_permlane32_swap_b32_e32 v169, v170
	v_permlane32_swap_b32_e32 v161, v168
	v_permlane32_swap_b32_e32 v159, v160
	v_permlane32_swap_b32_e32 v157, v158
	v_permlane32_swap_b32_e32 v154, v155
	v_ashrrev_i32_e32 v151, 31, v150
	v_pk_mul_f32 v[128:129], v[128:129], v[0:1] op_sel_hi:[1,0]
	v_pk_mul_f32 v[126:127], v[126:127], v[0:1] op_sel_hi:[1,0]
	v_pk_mul_f32 v[124:125], v[124:125], v[0:1] op_sel_hi:[1,0]
	v_pk_mul_f32 v[122:123], v[122:123], v[0:1] op_sel_hi:[1,0]
	v_cvt_pk_bf16_f32 v176, v126, v127
	v_cvt_pk_bf16_f32 v177, v128, v129
	v_pk_mul_f32 v[120:121], v[120:121], v[0:1] op_sel_hi:[1,0]
	v_cvt_pk_bf16_f32 v178, v122, v123
	v_cvt_pk_bf16_f32 v179, v124, v125
	v_pk_mul_f32 v[118:119], v[118:119], v[0:1] op_sel_hi:[1,0]
	v_pk_mul_f32 v[116:117], v[116:117], v[0:1] op_sel_hi:[1,0]
	v_pk_mul_f32 v[114:115], v[114:115], v[0:1] op_sel_hi:[1,0]
	s_cselect_b64 s[16:17], -1, 0
	s_cmp_lg_u32 s3, 4
	global_store_dwordx4 v[180:181], v[176:179], off
	s_nop 1
	v_cvt_pk_bf16_f32 v176, v118, v119
	v_cvt_pk_bf16_f32 v177, v120, v121
	v_cvt_pk_bf16_f32 v178, v114, v115
	v_cvt_pk_bf16_f32 v179, v116, v117
	global_store_dwordx4 v[180:181], v[176:179], off offset:256
	s_cbranch_scc1 .LBB0_514
	v_mul_f32_e32 v0, v127, v127
	v_mul_f32_e32 v123, v123, v123
	v_mul_f32_e32 v119, v119, v119
	v_mul_f32_e32 v115, v115, v115
	v_fmac_f32_e32 v0, v126, v126
	v_mul_f32_e32 v126, v129, v129
	v_fmac_f32_e32 v123, v122, v122
	v_mul_f32_e32 v122, v125, v125
	v_fmac_f32_e32 v119, v118, v118
	v_mul_f32_e32 v118, v121, v121
	v_fmac_f32_e32 v115, v114, v114
	v_mul_f32_e32 v114, v117, v117
	v_fmac_f32_e32 v126, v128, v128
	v_fmac_f32_e32 v122, v124, v124
	v_fmac_f32_e32 v118, v120, v120
	v_fmac_f32_e32 v114, v116, v116
	v_add_f32_e32 v0, v0, v126
	v_add_f32_e32 v122, v123, v122
	v_add_f32_e32 v118, v119, v118
	v_add_f32_e32 v114, v115, v114
	v_add_f32_e32 v0, v0, v122
	v_add_f32_e32 v115, v118, v114
	v_mov_b32_e32 v114, v0
	v_mov_b32_e32 v116, v115
	s_nop 0
	v_permlane16_swap_b32_e32 v0, v114
	v_permlane16_swap_b32_e32 v115, v116
	v_add_f32_e32 v0, v0, v114
	v_add_f32_e32 v115, v115, v116
	v_mov_b32_e32 v114, v0
	v_mov_b32_e32 v116, v115
	s_nop 0
	v_permlane32_swap_b32_e32 v0, v114
	v_permlane32_swap_b32_e32 v115, v116
	s_and_saveexec_b64 s[8:9], s[4:5]
	s_cbranch_execz .LBB0_513
	v_add_f32_e32 v116, v115, v116
	v_add_f32_e32 v0, v0, v114
	v_lshlrev_b64 v[114:115], 7, v[150:151]
	v_lshl_add_u64 v[114:115], v[138:139], 0, v[114:115]
	s_lshl_b32 s36, s2, 3
	s_mov_b32 s37, s40
	v_lshl_add_u64 v[114:115], s[36:37], 2, v[114:115]
	s_lshl_b32 s36, s27, 2
	v_lshl_add_u64 v[114:115], v[114:115], 0, s[36:37]
	global_store_dword v[114:115], v0, off offset:-128
	global_store_dword v[114:115], v116, off offset:-112

.LBB0_1086:
	v_lshl_or_b32 v216, s12, 8, v250
	v_lshl_add_u32 v232, s28, 8, v238
	v_ashrrev_i32_e32 v217, 31, v216
	v_lshlrev_b64 v[234:235], 1, v[216:217]
	v_ashrrev_i32_e32 v233, 31, v232
	v_lshl_add_u64 v[134:135], v[202:203], 0, v[234:235]
	v_lshlrev_b64 v[236:237], 12, v[232:233]
	v_lshl_add_u64 v[130:131], v[134:135], 0, v[236:237]
	global_load_dwordx4 v[190:193], v[130:131], off
	global_load_dwordx4 v[186:189], v[130:131], off offset:256
	v_or_b32_e32 v230, 16, v232
	v_ashrrev_i32_e32 v231, 31, v230
	v_lshlrev_b64 v[130:131], 12, v[230:231]
	v_or_b32_e32 v228, 32, v232
	v_lshl_add_u64 v[130:131], v[134:135], 0, v[130:131]
	v_ashrrev_i32_e32 v229, 31, v228
	global_load_dwordx4 v[182:185], v[130:131], off
	global_load_dwordx4 v[178:181], v[130:131], off offset:256
	v_lshlrev_b64 v[130:131], 12, v[228:229]
	v_or_b32_e32 v226, 48, v232
	v_lshl_add_u64 v[130:131], v[134:135], 0, v[130:131]
	v_ashrrev_i32_e32 v227, 31, v226
	global_load_dwordx4 v[174:177], v[130:131], off
	global_load_dwordx4 v[170:173], v[130:131], off offset:256
	v_lshlrev_b64 v[130:131], 12, v[226:227]
	v_add_u32_e32 v224, 0x80, v232
	v_lshl_add_u64 v[130:131], v[134:135], 0, v[130:131]
	v_ashrrev_i32_e32 v225, 31, v224
	global_load_dwordx4 v[166:169], v[130:131], off
	global_load_dwordx4 v[162:165], v[130:131], off offset:256
	v_lshlrev_b64 v[130:131], 12, v[224:225]
	v_add_u32_e32 v222, 0x90, v232
	v_lshl_add_u64 v[130:131], v[134:135], 0, v[130:131]
	v_ashrrev_i32_e32 v223, 31, v222
	global_load_dwordx4 v[158:161], v[130:131], off
	global_load_dwordx4 v[154:157], v[130:131], off offset:256
	v_lshlrev_b64 v[130:131], 12, v[222:223]
	v_add_u32_e32 v220, 0xa0, v232
	v_add_u32_e32 v218, 0xb0, v232
	v_lshl_add_u64 v[130:131], v[134:135], 0, v[130:131]
	v_ashrrev_i32_e32 v221, 31, v220
	v_ashrrev_i32_e32 v219, 31, v218
	global_load_dwordx4 v[150:153], v[130:131], off
	global_load_dwordx4 v[146:149], v[130:131], off offset:256
	v_lshlrev_b64 v[130:131], 12, v[220:221]
	v_lshlrev_b64 v[136:137], 12, v[218:219]
	v_lshl_add_u64 v[130:131], v[134:135], 0, v[130:131]
	v_lshl_add_u64 v[134:135], v[134:135], 0, v[136:137]
	global_load_dwordx4 v[138:141], v[130:131], off
	s_nop 0
	global_load_dwordx4 v[130:133], v[130:131], off offset:256
	s_nop 0
	global_load_dwordx4 v[142:145], v[134:135], off
	s_nop 0
	global_load_dwordx4 v[134:137], v[134:135], off offset:256
	s_mov_b64 vcc, s[2:3]
	s_cbranch_vccz .Lalign_skip_4
	s_barrier
.Lalign_skip_4:
	s_lshl_b32 s8, s12, 2
	s_ashr_i32 s9, s8, 31
	s_waitcnt vmcnt(0)
	v_lshlrev_b32_e32 v252, 16, v190
	v_and_b32_e32 v253, 0xffff0000, v190
	v_lshlrev_b32_e32 v190, 16, v191
	v_and_b32_e32 v191, 0xffff0000, v191
	v_pk_add_f32 v[124:125], v[124:125], v[190:191]
	v_pk_add_f32 v[122:123], v[122:123], v[252:253]
	v_lshlrev_b32_e32 v206, 16, v192
	v_and_b32_e32 v207, 0xffff0000, v192
	v_mul_f32_e32 v0, v123, v123
	v_mul_f32_e32 v190, v125, v125
	v_pk_add_f32 v[126:127], v[126:127], v[206:207]
	v_fmac_f32_e32 v0, v122, v122
	v_fmac_f32_e32 v190, v124, v124
	v_add_f32_e32 v0, v0, v190
	v_mul_f32_e32 v190, v127, v127
	v_lshlrev_b32_e32 v192, 16, v193
	v_and_b32_e32 v193, 0xffff0000, v193
	v_fmac_f32_e32 v190, v126, v126
	v_cvt_pk_bf16_f32 v122, v122, v123
	v_cvt_pk_bf16_f32 v123, v124, v125
	v_cvt_pk_bf16_f32 v124, v126, v127
	v_lshl_add_u64 v[126:127], v[202:203], 0, v[236:237]
	v_pk_add_f32 v[128:129], v[128:129], v[192:193]
	v_lshl_add_u64 v[126:127], v[126:127], 0, v[234:235]
	v_cvt_pk_bf16_f32 v125, v128, v129
	v_mul_f32_e32 v191, v129, v129
	global_store_dwordx4 v[126:127], v[122:125], off
	v_fmac_f32_e32 v191, v128, v128
	v_lshlrev_b32_e32 v128, 16, v188
	v_lshlrev_b32_e32 v122, 16, v186
	v_and_b32_e32 v123, 0xffff0000, v186
	v_lshlrev_b32_e32 v124, 16, v187
	v_and_b32_e32 v125, 0xffff0000, v187
	v_and_b32_e32 v129, 0xffff0000, v188
	v_lshlrev_b32_e32 v186, 16, v189
	v_and_b32_e32 v187, 0xffff0000, v189
	v_pk_add_f32 v[120:121], v[120:121], v[124:125]
	v_pk_add_f32 v[118:119], v[118:119], v[122:123]
	v_pk_add_f32 v[122:123], v[116:117], v[186:187]
	v_pk_add_f32 v[116:117], v[114:115], v[128:129]
	v_mul_f32_e32 v114, v119, v119
	v_mul_f32_e32 v115, v121, v121
	v_fmac_f32_e32 v114, v118, v118
	v_fmac_f32_e32 v115, v120, v120
	v_add_f32_e32 v114, v114, v115
	v_mul_f32_e32 v115, v117, v117
	v_mul_f32_e32 v124, v123, v123
	v_fmac_f32_e32 v115, v116, v116
	v_fmac_f32_e32 v124, v122, v122
	v_add_f32_e32 v190, v190, v191
	v_add_f32_e32 v115, v115, v124
	v_add_f32_e32 v0, v0, v190
	v_add_f32_e32 v114, v114, v115
	v_add_f32_e32 v0, v0, v114
	v_cvt_pk_bf16_f32 v114, v118, v119
	v_cvt_pk_bf16_f32 v115, v120, v121
	v_cvt_pk_bf16_f32 v116, v116, v117
	v_cvt_pk_bf16_f32 v117, v122, v123
	global_store_dwordx4 v[126:127], v[114:117], off offset:256
	s_nop 1
	v_mov_b32_e32 v114, v0
	s_nop 1
	v_permlane16_swap_b32_e32 v0, v114
	v_add_f32_e32 v0, v0, v114
	v_mov_b32_e32 v114, v0
	s_nop 1
	v_permlane32_swap_b32_e32 v0, v114
	s_and_saveexec_b64 s[12:13], s[4:5]
	s_cbranch_execz .LBB0_1088
	v_lshlrev_b64 v[116:117], 6, v[232:233]
	v_lshl_add_u64 v[116:117], v[204:205], 0, v[116:117]
	v_lshl_add_u64 v[116:117], s[8:9], 1, v[116:117]
	s_lshl_b32 s28, s23, 1
	s_mov_b32 s29, s40
	v_lshl_add_u64 v[116:117], v[116:117], 0, s[28:29]
	v_add_f32_e32 v0, v0, v114
	v_cvt_pk_bf16_f32 v0, v0, v1
	global_store_short v[116:117], v0, off

.LBB0_1167:
.LBB0_1169:
	ds_read_b128 v[150:153], v170
	ds_read_b128 v[154:157], v170 offset:2048
	v_add_u32_e32 v148, s7, v161
	v_lshl_or_b32 v164, s11, 8, v168
	v_ashrrev_i32_e32 v165, 31, v164
	s_waitcnt lgkmcnt(0)
	v_lshlrev_b32_e32 v0, 16, v150
	v_and_b32_e32 v149, 0xffff0000, v150
	v_add_f32_e32 v0, v0, v149
	v_lshlrev_b32_e32 v149, 16, v151
	v_and_b32_e32 v150, 0xffff0000, v151
	v_add_f32_e32 v149, v149, v150
	v_add_f32_e32 v0, v0, v149
	v_lshlrev_b32_e32 v149, 16, v152
	v_and_b32_e32 v150, 0xffff0000, v152
	v_add_f32_e32 v149, v149, v150
	v_lshlrev_b32_e32 v150, 16, v153
	v_and_b32_e32 v151, 0xffff0000, v153
	v_add_f32_e32 v150, v150, v151
	v_add_f32_e32 v149, v149, v150
	v_add_f32_e32 v0, v0, v149
	v_mov_b32_e32 v149, v0
	ds_read_b128 v[150:153], v170 offset:1024
	ds_read_b128 v[172:175], v170 offset:8192
	v_permlane16_swap_b32_e32 v0, v149
	v_add_f32_e32 v0, v0, v149
	v_mov_b32_e32 v149, v0
	s_nop 1
	v_permlane32_swap_b32_e32 v0, v149
	v_add_f32_e32 v0, v0, v149
	s_waitcnt lgkmcnt(0)
	v_lshlrev_b32_e32 v149, 16, v150
	v_and_b32_e32 v150, 0xffff0000, v150
	v_add_f32_e32 v149, v149, v150
	v_lshlrev_b32_e32 v150, 16, v151
	v_and_b32_e32 v151, 0xffff0000, v151
	v_add_f32_e32 v150, v150, v151
	v_add_f32_e32 v149, v149, v150
	v_lshlrev_b32_e32 v150, 16, v152
	v_and_b32_e32 v151, 0xffff0000, v152
	v_add_f32_e32 v150, v150, v151
	v_lshlrev_b32_e32 v151, 16, v153
	v_and_b32_e32 v152, 0xffff0000, v153
	v_add_f32_e32 v151, v151, v152
	v_add_f32_e32 v150, v150, v151
	v_add_f32_e32 v149, v149, v150
	v_mov_b32_e32 v150, v149
	s_nop 1
	v_permlane16_swap_b32_e32 v149, v150
	v_add_f32_e32 v149, v149, v150
	v_mov_b32_e32 v150, v149
	s_nop 1
	v_permlane32_swap_b32_e32 v149, v150
	v_add_f32_e32 v149, v149, v150
	v_fmamk_f32 v149, v149, 0x3a000000, v240
	v_rsq_f32_e32 v152, v149
	v_lshlrev_b32_e32 v149, 16, v154
	v_and_b32_e32 v150, 0xffff0000, v154
	v_add_f32_e32 v149, v149, v150
	v_lshlrev_b32_e32 v150, 16, v155
	v_and_b32_e32 v151, 0xffff0000, v155
	v_add_f32_e32 v150, v150, v151
	v_add_f32_e32 v149, v149, v150
	v_lshlrev_b32_e32 v150, 16, v156
	v_and_b32_e32 v151, 0xffff0000, v156
	v_add_f32_e32 v150, v150, v151
	v_lshlrev_b32_e32 v151, 16, v157
	v_and_b32_e32 v153, 0xffff0000, v157
	v_add_f32_e32 v151, v151, v153
	v_add_f32_e32 v150, v150, v151
	v_add_f32_e32 v149, v149, v150
	v_mov_b32_e32 v150, v149
	s_nop 1
	v_permlane16_swap_b32_e32 v149, v150
	v_add_f32_e32 v149, v149, v150
	ds_read_b128 v[154:157], v170 offset:3072
	v_mov_b32_e32 v150, v149
	s_nop 1
	v_permlane32_swap_b32_e32 v149, v150
	v_add_f32_e32 v149, v149, v150
	v_fmamk_f32 v149, v149, 0x3a000000, v240
	v_rsq_f32_e32 v150, v149
	s_waitcnt lgkmcnt(0)
	v_lshlrev_b32_e32 v149, 16, v154
	v_and_b32_e32 v151, 0xffff0000, v154
	v_add_f32_e32 v149, v149, v151
	v_lshlrev_b32_e32 v151, 16, v155
	v_and_b32_e32 v153, 0xffff0000, v155
	v_add_f32_e32 v151, v151, v153
	v_add_f32_e32 v149, v149, v151
	v_lshlrev_b32_e32 v151, 16, v156
	v_and_b32_e32 v153, 0xffff0000, v156
	v_add_f32_e32 v151, v151, v153
	v_lshlrev_b32_e32 v153, 16, v157
	v_and_b32_e32 v154, 0xffff0000, v157
	v_add_f32_e32 v153, v153, v154
	v_add_f32_e32 v151, v151, v153
	v_add_f32_e32 v149, v149, v151
	v_mov_b32_e32 v151, v149
	s_nop 1
	v_permlane16_swap_b32_e32 v149, v151
	v_add_f32_e32 v149, v149, v151
	v_mov_b32_e32 v151, v149
	s_nop 1
	v_permlane32_swap_b32_e32 v149, v151
	v_add_f32_e32 v149, v149, v151
	v_fmamk_f32 v149, v149, 0x3a000000, v240
	v_rsq_f32_e32 v156, v149
	v_lshlrev_b32_e32 v149, 16, v172
	v_and_b32_e32 v151, 0xffff0000, v172
	s_mov_b64 vcc, s[2:3]
	s_cbranch_vccz .Lalign_skip_2
	s_barrier
.Lalign_skip_2:
	v_add_f32_e32 v149, v149, v151
	v_lshlrev_b32_e32 v151, 16, v173
	v_and_b32_e32 v153, 0xffff0000, v173
	v_add_f32_e32 v151, v151, v153
	v_add_f32_e32 v149, v149, v151
	v_lshlrev_b32_e32 v151, 16, v174
	v_and_b32_e32 v153, 0xffff0000, v174
	v_add_f32_e32 v151, v151, v153
	v_lshlrev_b32_e32 v153, 16, v175
	v_and_b32_e32 v154, 0xffff0000, v175
	v_add_f32_e32 v153, v153, v154
	v_add_f32_e32 v151, v151, v153
	v_add_f32_e32 v149, v149, v151
	v_mov_b32_e32 v151, v149
	s_nop 1
	v_permlane16_swap_b32_e32 v149, v151
	v_add_f32_e32 v149, v149, v151
	ds_read_b128 v[172:175], v170 offset:9216
	v_mov_b32_e32 v151, v149
	s_nop 1
	v_permlane32_swap_b32_e32 v149, v151
	v_add_f32_e32 v149, v149, v151
	v_fmamk_f32 v149, v149, 0x3a000000, v240
	v_rsq_f32_e32 v154, v149
	s_waitcnt lgkmcnt(0)
	v_lshlrev_b32_e32 v149, 16, v172
	v_and_b32_e32 v151, 0xffff0000, v172
	v_add_f32_e32 v149, v149, v151
	v_lshlrev_b32_e32 v151, 16, v173
	v_and_b32_e32 v153, 0xffff0000, v173
	v_add_f32_e32 v151, v151, v153
	v_add_f32_e32 v149, v149, v151
	v_lshlrev_b32_e32 v151, 16, v174
	v_and_b32_e32 v153, 0xffff0000, v174
	v_add_f32_e32 v151, v151, v153
	v_lshlrev_b32_e32 v153, 16, v175
	v_and_b32_e32 v155, 0xffff0000, v175
	v_add_f32_e32 v153, v153, v155
	v_add_f32_e32 v151, v151, v153
	v_add_f32_e32 v149, v149, v151
	v_mov_b32_e32 v151, v149
	s_nop 1
	v_permlane16_swap_b32_e32 v149, v151
	v_add_f32_e32 v149, v149, v151
	ds_read_b128 v[172:175], v170 offset:10240
	v_mov_b32_e32 v151, v149
	s_nop 1
	v_permlane32_swap_b32_e32 v149, v151
	v_add_f32_e32 v149, v149, v151
	v_fmamk_f32 v149, v149, 0x3a000000, v240
	v_rsq_f32_e32 v160, v149
	s_waitcnt lgkmcnt(0)
	v_lshlrev_b32_e32 v149, 16, v172
	v_and_b32_e32 v151, 0xffff0000, v172
	v_add_f32_e32 v149, v149, v151
	v_lshlrev_b32_e32 v151, 16, v173
	v_and_b32_e32 v153, 0xffff0000, v173
	v_add_f32_e32 v151, v151, v153
	v_add_f32_e32 v149, v149, v151
	v_lshlrev_b32_e32 v151, 16, v174
	v_and_b32_e32 v153, 0xffff0000, v174
	v_add_f32_e32 v151, v151, v153
	v_lshlrev_b32_e32 v153, 16, v175
	v_and_b32_e32 v155, 0xffff0000, v175
	v_add_f32_e32 v153, v153, v155
	v_add_f32_e32 v151, v151, v153
	v_add_f32_e32 v149, v149, v151
	v_mov_b32_e32 v151, v149
	s_nop 1
	v_permlane16_swap_b32_e32 v149, v151
	v_add_f32_e32 v149, v149, v151
	ds_read_b128 v[172:175], v170 offset:11264
	v_mov_b32_e32 v151, v149
	s_nop 1
	v_permlane32_swap_b32_e32 v149, v151
	v_add_f32_e32 v149, v149, v151
	v_fmamk_f32 v149, v149, 0x3a000000, v240
	v_rsq_f32_e32 v158, v149
	s_waitcnt lgkmcnt(0)
	v_lshlrev_b32_e32 v149, 16, v172
	v_and_b32_e32 v151, 0xffff0000, v172
	v_add_f32_e32 v149, v149, v151
	v_lshlrev_b32_e32 v151, 16, v173
	v_and_b32_e32 v153, 0xffff0000, v173
	v_add_f32_e32 v151, v151, v153
	v_add_f32_e32 v149, v149, v151
	v_lshlrev_b32_e32 v151, 16, v174
	v_and_b32_e32 v153, 0xffff0000, v174
	v_add_f32_e32 v151, v151, v153
	v_lshlrev_b32_e32 v153, 16, v175
	v_and_b32_e32 v155, 0xffff0000, v175
	v_add_f32_e32 v153, v153, v155
	v_add_f32_e32 v151, v151, v153
	v_add_f32_e32 v149, v149, v151
	v_mov_b32_e32 v151, v149
	v_fmamk_f32 v0, v0, 0x3a000000, v240
	s_nop 0
	v_permlane16_swap_b32_e32 v149, v151
	v_rsq_f32_e32 v0, v0
	v_add_f32_e32 v149, v149, v151
	v_mov_b32_e32 v151, v149
	s_nop 1
	v_permlane32_swap_b32_e32 v149, v151
	v_add_f32_e32 v149, v149, v151
	v_fmamk_f32 v149, v149, 0x3a000000, v240
	v_pk_mul_f32 v[122:123], v[122:123], v[0:1] op_sel_hi:[1,0]
	v_rsq_f32_e32 v162, v149
	v_ashrrev_i32_e32 v149, 31, v148
	v_max_f32_e32 v122, 0, v122
	v_lshl_add_u64 v[172:173], v[164:165], 1, v[138:139]
	v_lshlrev_b64 v[164:165], 14, v[148:149]
	v_pk_mul_f32 v[124:125], v[124:125], v[0:1] op_sel_hi:[1,0]
	v_mul_f32_e32 v149, v122, v122
	v_max_f32_e32 v122, 0, v123
	v_pk_mul_f32 v[126:127], v[126:127], v[0:1] op_sel_hi:[1,0]
	v_mul_f32_e32 v151, v122, v122
	v_max_f32_e32 v122, 0, v124
	v_pk_mul_f32 v[114:115], v[114:115], v[0:1] op_sel_hi:[1,0]
	v_pk_mul_f32 v[128:129], v[128:129], v[0:1] op_sel_hi:[1,0]
	v_max_f32_e32 v126, 0, v126
	v_max_f32_e32 v127, 0, v127
	v_mul_f32_e32 v153, v122, v122
	v_max_f32_e32 v122, 0, v125
	v_pk_mul_f32 v[120:121], v[120:121], v[0:1] op_sel_hi:[1,0]
	v_pk_mul_f32 v[118:119], v[118:119], v[0:1] op_sel_hi:[1,0]
	v_max_f32_e32 v114, 0, v114
	v_lshl_add_u64 v[164:165], v[172:173], 0, v[164:165]
	v_mul_f32_e32 v126, v126, v126
	v_mul_f32_e32 v127, v127, v127
	v_max_f32_e32 v128, 0, v128
	v_max_f32_e32 v129, 0, v129
	v_mul_f32_e32 v125, v122, v122
	v_cvt_pk_bf16_f32 v122, v126, v127
	v_pk_mul_f32 v[116:117], v[116:117], v[0:1] op_sel_hi:[1,0]
	v_max_f32_e32 v0, 0, v118
	v_max_f32_e32 v118, 0, v119
	v_max_f32_e32 v119, 0, v120
	v_max_f32_e32 v120, 0, v121
	v_mul_f32_e32 v121, v114, v114
	v_max_f32_e32 v114, 0, v115
	v_mul_f32_e32 v128, v128, v128
	v_mul_f32_e32 v129, v129, v129
	v_cvt_pk_bf16_f32 v123, v128, v129
	v_cvt_pk_bf16_f32 v124, v149, v151
	v_cvt_pk_bf16_f32 v125, v153, v125
	global_store_dwordx4 v[164:165], v[122:125], off
	v_pk_mul_f32 v[106:107], v[106:107], v[152:153] op_sel_hi:[1,0]
	v_mul_f32_e32 v0, v0, v0
	v_mul_f32_e32 v122, v114, v114
	v_max_f32_e32 v114, 0, v116
	v_mul_f32_e32 v123, v114, v114
	v_max_f32_e32 v114, 0, v117
	v_mul_f32_e32 v118, v118, v118
	v_mul_f32_e32 v117, v114, v114
	v_cvt_pk_bf16_f32 v114, v0, v118
	v_pk_mul_f32 v[112:113], v[112:113], v[152:153] op_sel_hi:[1,0]
	v_pk_mul_f32 v[110:111], v[110:111], v[152:153] op_sel_hi:[1,0]
	v_max_f32_e32 v106, 0, v106
	v_mul_f32_e32 v119, v119, v119
	v_mul_f32_e32 v120, v120, v120
	v_cvt_pk_bf16_f32 v115, v119, v120
	v_cvt_pk_bf16_f32 v116, v121, v122
	v_cvt_pk_bf16_f32 v117, v123, v117
	global_store_dwordx4 v[164:165], v[114:117], off offset:256
	v_pk_mul_f32 v[108:109], v[108:109], v[152:153] op_sel_hi:[1,0]
	v_max_f32_e32 v0, 0, v110
	v_or_b32_e32 v114, 16, v148
	v_max_f32_e32 v110, 0, v111
	v_max_f32_e32 v111, 0, v112
	v_max_f32_e32 v112, 0, v113
	v_mul_f32_e32 v113, v106, v106
	v_max_f32_e32 v106, 0, v107
	v_ashrrev_i32_e32 v115, 31, v114
	v_mul_f32_e32 v116, v106, v106
	v_max_f32_e32 v106, 0, v108
	v_pk_mul_f32 v[98:99], v[98:99], v[152:153] op_sel_hi:[1,0]
	v_lshlrev_b64 v[114:115], 14, v[114:115]
	v_mul_f32_e32 v0, v0, v0
	v_mul_f32_e32 v117, v106, v106
	v_max_f32_e32 v106, 0, v109
	v_pk_mul_f32 v[104:105], v[104:105], v[152:153] op_sel_hi:[1,0]
	v_pk_mul_f32 v[102:103], v[102:103], v[152:153] op_sel_hi:[1,0]
	v_max_f32_e32 v98, 0, v98
	v_lshl_add_u64 v[114:115], v[172:173], 0, v[114:115]
	v_mul_f32_e32 v110, v110, v110
	v_mul_f32_e32 v109, v106, v106
	v_cvt_pk_bf16_f32 v106, v0, v110
	v_pk_mul_f32 v[100:101], v[100:101], v[152:153] op_sel_hi:[1,0]
	v_max_f32_e32 v0, 0, v102
	v_max_f32_e32 v102, 0, v103
	v_max_f32_e32 v103, 0, v104
	v_max_f32_e32 v104, 0, v105
	v_mul_f32_e32 v105, v98, v98
	v_max_f32_e32 v98, 0, v99
	v_mul_f32_e32 v111, v111, v111
	v_mul_f32_e32 v112, v112, v112
	v_cvt_pk_bf16_f32 v107, v111, v112
	v_cvt_pk_bf16_f32 v108, v113, v116
	v_cvt_pk_bf16_f32 v109, v117, v109
	global_store_dwordx4 v[114:115], v[106:109], off
	v_pk_mul_f32 v[90:91], v[90:91], v[150:151] op_sel_hi:[1,0]
	v_mul_f32_e32 v0, v0, v0
	v_mul_f32_e32 v106, v98, v98
	v_max_f32_e32 v98, 0, v100
	v_mul_f32_e32 v107, v98, v98
	v_max_f32_e32 v98, 0, v101
	v_mul_f32_e32 v102, v102, v102
	v_mul_f32_e32 v101, v98, v98
	v_cvt_pk_bf16_f32 v98, v0, v102
	v_pk_mul_f32 v[96:97], v[96:97], v[150:151] op_sel_hi:[1,0]
	v_pk_mul_f32 v[94:95], v[94:95], v[150:151] op_sel_hi:[1,0]
	v_max_f32_e32 v90, 0, v90
	v_mul_f32_e32 v103, v103, v103
	v_mul_f32_e32 v104, v104, v104
	v_cvt_pk_bf16_f32 v99, v103, v104
	v_cvt_pk_bf16_f32 v100, v105, v106
	v_cvt_pk_bf16_f32 v101, v107, v101
	global_store_dwordx4 v[114:115], v[98:101], off offset:256
	v_pk_mul_f32 v[92:93], v[92:93], v[150:151] op_sel_hi:[1,0]
	v_max_f32_e32 v0, 0, v94
	v_or_b32_e32 v98, 32, v148
	v_max_f32_e32 v94, 0, v95
	v_max_f32_e32 v95, 0, v96
	v_max_f32_e32 v96, 0, v97
	v_mul_f32_e32 v97, v90, v90
	v_max_f32_e32 v90, 0, v91
	v_ashrrev_i32_e32 v99, 31, v98
	v_mul_f32_e32 v100, v90, v90
	v_max_f32_e32 v90, 0, v92
	v_pk_mul_f32 v[82:83], v[82:83], v[150:151] op_sel_hi:[1,0]
	v_lshlrev_b64 v[98:99], 14, v[98:99]
	v_mul_f32_e32 v0, v0, v0
	v_mul_f32_e32 v101, v90, v90
	v_max_f32_e32 v90, 0, v93
	v_pk_mul_f32 v[88:89], v[88:89], v[150:151] op_sel_hi:[1,0]
	v_pk_mul_f32 v[86:87], v[86:87], v[150:151] op_sel_hi:[1,0]
	v_max_f32_e32 v82, 0, v82
	v_lshl_add_u64 v[98:99], v[172:173], 0, v[98:99]
	v_mul_f32_e32 v94, v94, v94
	v_mul_f32_e32 v93, v90, v90
	v_cvt_pk_bf16_f32 v90, v0, v94
	v_pk_mul_f32 v[84:85], v[84:85], v[150:151] op_sel_hi:[1,0]
	v_max_f32_e32 v0, 0, v86
	v_max_f32_e32 v86, 0, v87
	v_max_f32_e32 v87, 0, v88
	v_max_f32_e32 v88, 0, v89
	v_mul_f32_e32 v89, v82, v82
	v_max_f32_e32 v82, 0, v83
	v_mul_f32_e32 v95, v95, v95
	v_mul_f32_e32 v96, v96, v96
	v_cvt_pk_bf16_f32 v91, v95, v96
	v_cvt_pk_bf16_f32 v92, v97, v100
	v_cvt_pk_bf16_f32 v93, v101, v93
	global_store_dwordx4 v[98:99], v[90:93], off
	v_pk_mul_f32 v[74:75], v[74:75], v[156:157] op_sel_hi:[1,0]
	v_mul_f32_e32 v0, v0, v0
	v_mul_f32_e32 v90, v82, v82
	v_max_f32_e32 v82, 0, v84
	v_mul_f32_e32 v91, v82, v82
	v_max_f32_e32 v82, 0, v85
	v_mul_f32_e32 v86, v86, v86
	v_mul_f32_e32 v85, v82, v82
	v_cvt_pk_bf16_f32 v82, v0, v86
	v_pk_mul_f32 v[80:81], v[80:81], v[156:157] op_sel_hi:[1,0]
	v_pk_mul_f32 v[78:79], v[78:79], v[156:157] op_sel_hi:[1,0]
	v_max_f32_e32 v74, 0, v74
	v_mul_f32_e32 v87, v87, v87
	v_mul_f32_e32 v88, v88, v88
	v_cvt_pk_bf16_f32 v83, v87, v88
	v_cvt_pk_bf16_f32 v84, v89, v90
	v_cvt_pk_bf16_f32 v85, v91, v85
	global_store_dwordx4 v[98:99], v[82:85], off offset:256
	v_pk_mul_f32 v[76:77], v[76:77], v[156:157] op_sel_hi:[1,0]
	v_max_f32_e32 v0, 0, v78
	v_or_b32_e32 v82, 48, v148
	v_max_f32_e32 v78, 0, v79
	v_max_f32_e32 v79, 0, v80
	v_max_f32_e32 v80, 0, v81
	v_mul_f32_e32 v81, v74, v74
	v_max_f32_e32 v74, 0, v75
	v_ashrrev_i32_e32 v83, 31, v82
	v_mul_f32_e32 v84, v74, v74
	v_max_f32_e32 v74, 0, v76
	v_pk_mul_f32 v[66:67], v[66:67], v[156:157] op_sel_hi:[1,0]
	v_lshlrev_b64 v[82:83], 14, v[82:83]
	v_mul_f32_e32 v0, v0, v0
	v_mul_f32_e32 v85, v74, v74
	v_max_f32_e32 v74, 0, v77
	v_pk_mul_f32 v[72:73], v[72:73], v[156:157] op_sel_hi:[1,0]
	v_pk_mul_f32 v[70:71], v[70:71], v[156:157] op_sel_hi:[1,0]
	v_max_f32_e32 v66, 0, v66
	v_lshl_add_u64 v[82:83], v[172:173], 0, v[82:83]
	v_mul_f32_e32 v78, v78, v78
	v_mul_f32_e32 v77, v74, v74
	v_cvt_pk_bf16_f32 v74, v0, v78
	v_pk_mul_f32 v[68:69], v[68:69], v[156:157] op_sel_hi:[1,0]
	v_max_f32_e32 v0, 0, v70
	v_max_f32_e32 v70, 0, v71
	v_max_f32_e32 v71, 0, v72
	v_max_f32_e32 v72, 0, v73
	v_mul_f32_e32 v73, v66, v66
	v_max_f32_e32 v66, 0, v67
	v_mul_f32_e32 v79, v79, v79
	v_mul_f32_e32 v80, v80, v80
	v_cvt_pk_bf16_f32 v75, v79, v80
	v_cvt_pk_bf16_f32 v76, v81, v84
	v_cvt_pk_bf16_f32 v77, v85, v77
	global_store_dwordx4 v[82:83], v[74:77], off
	v_pk_mul_f32 v[58:59], v[58:59], v[154:155] op_sel_hi:[1,0]
	v_mul_f32_e32 v0, v0, v0
	v_mul_f32_e32 v74, v66, v66
	v_max_f32_e32 v66, 0, v68
	v_mul_f32_e32 v75, v66, v66
	v_max_f32_e32 v66, 0, v69
	v_pk_mul_f32 v[64:65], v[64:65], v[154:155] op_sel_hi:[1,0]
	v_pk_mul_f32 v[62:63], v[62:63], v[154:155] op_sel_hi:[1,0]
	v_max_f32_e32 v58, 0, v58
	v_mul_f32_e32 v70, v70, v70
	v_mul_f32_e32 v71, v71, v71
	v_mul_f32_e32 v72, v72, v72
	v_mul_f32_e32 v69, v66, v66
	v_cvt_pk_bf16_f32 v66, v0, v70
	v_cvt_pk_bf16_f32 v67, v71, v72
	v_cvt_pk_bf16_f32 v68, v73, v74
	v_pk_mul_f32 v[60:61], v[60:61], v[154:155] op_sel_hi:[1,0]
	v_max_f32_e32 v0, 0, v62
	v_max_f32_e32 v62, 0, v63
	v_max_f32_e32 v63, 0, v64
	v_max_f32_e32 v64, 0, v65
	v_mul_f32_e32 v65, v58, v58
	v_max_f32_e32 v58, 0, v59
	v_cvt_pk_bf16_f32 v69, v75, v69
	global_store_dwordx4 v[82:83], v[66:69], off offset:256
	v_mul_f32_e32 v62, v62, v62
	s_mov_b32 s7, 0x200000
	v_mul_f32_e32 v68, v58, v58
	v_max_f32_e32 v58, 0, v60
	v_mul_f32_e32 v69, v58, v58
	v_max_f32_e32 v58, 0, v61
	v_pk_mul_f32 v[50:51], v[50:51], v[154:155] op_sel_hi:[1,0]
	v_mul_f32_e32 v0, v0, v0
	v_mul_f32_e32 v63, v63, v63
	v_mul_f32_e32 v61, v58, v58
	v_cvt_pk_bf16_f32 v58, v0, v62
	v_add_co_u32_e32 v62, vcc, s7, v164
	v_pk_mul_f32 v[56:57], v[56:57], v[154:155] op_sel_hi:[1,0]
	v_pk_mul_f32 v[54:55], v[54:55], v[154:155] op_sel_hi:[1,0]
	v_max_f32_e32 v50, 0, v50
	v_mul_f32_e32 v64, v64, v64
	v_cvt_pk_bf16_f32 v59, v63, v64
	v_addc_co_u32_e32 v63, vcc, 0, v165, vcc
	v_pk_mul_f32 v[52:53], v[52:53], v[154:155] op_sel_hi:[1,0]
	v_max_f32_e32 v0, 0, v54
	v_max_f32_e32 v54, 0, v55
	v_max_f32_e32 v55, 0, v56
	v_max_f32_e32 v56, 0, v57
	v_mul_f32_e32 v57, v50, v50
	v_max_f32_e32 v50, 0, v51
	v_cvt_pk_bf16_f32 v60, v65, v68
	v_cvt_pk_bf16_f32 v61, v69, v61
	global_store_dwordx4 v[62:63], v[58:61], off
	v_pk_mul_f32 v[42:43], v[42:43], v[160:161] op_sel_hi:[1,0]
	v_mul_f32_e32 v0, v0, v0
	v_mul_f32_e32 v58, v50, v50
	v_max_f32_e32 v50, 0, v52
	v_mul_f32_e32 v59, v50, v50
	v_max_f32_e32 v50, 0, v53
	v_pk_mul_f32 v[48:49], v[48:49], v[160:161] op_sel_hi:[1,0]
	v_pk_mul_f32 v[46:47], v[46:47], v[160:161] op_sel_hi:[1,0]
	v_max_f32_e32 v42, 0, v42
	v_lshl_add_u64 v[66:67], v[164:165], 0, s[50:51]
	v_mul_f32_e32 v54, v54, v54
	v_mul_f32_e32 v55, v55, v55
	v_mul_f32_e32 v56, v56, v56
	v_mul_f32_e32 v53, v50, v50
	v_cvt_pk_bf16_f32 v50, v0, v54
	v_cvt_pk_bf16_f32 v51, v55, v56
	v_cvt_pk_bf16_f32 v52, v57, v58
	v_pk_mul_f32 v[44:45], v[44:45], v[160:161] op_sel_hi:[1,0]
	v_max_f32_e32 v0, 0, v46
	v_max_f32_e32 v46, 0, v47
	v_max_f32_e32 v47, 0, v48
	v_max_f32_e32 v48, 0, v49
	v_mul_f32_e32 v49, v42, v42
	v_max_f32_e32 v42, 0, v43
	v_cvt_pk_bf16_f32 v53, v59, v53
	global_store_dwordx4 v[66:67], v[50:53], off offset:256
	v_mul_f32_e32 v46, v46, v46
	s_mov_b32 s7, 0x240000
	v_mul_f32_e32 v52, v42, v42
	v_max_f32_e32 v42, 0, v44
	v_mul_f32_e32 v53, v42, v42
	v_max_f32_e32 v42, 0, v45
	v_pk_mul_f32 v[34:35], v[34:35], v[160:161] op_sel_hi:[1,0]
	v_mul_f32_e32 v0, v0, v0
	v_mul_f32_e32 v47, v47, v47
	v_mul_f32_e32 v45, v42, v42
	v_cvt_pk_bf16_f32 v42, v0, v46
	v_add_co_u32_e32 v46, vcc, s7, v164
	v_pk_mul_f32 v[40:41], v[40:41], v[160:161] op_sel_hi:[1,0]
	v_pk_mul_f32 v[38:39], v[38:39], v[160:161] op_sel_hi:[1,0]
	v_max_f32_e32 v34, 0, v34
	v_mul_f32_e32 v48, v48, v48
	v_cvt_pk_bf16_f32 v43, v47, v48
	v_addc_co_u32_e32 v47, vcc, 0, v165, vcc
	v_pk_mul_f32 v[36:37], v[36:37], v[160:161] op_sel_hi:[1,0]
	v_max_f32_e32 v0, 0, v38
	v_max_f32_e32 v38, 0, v39
	v_max_f32_e32 v39, 0, v40
	v_max_f32_e32 v40, 0, v41
	v_mul_f32_e32 v41, v34, v34
	v_max_f32_e32 v34, 0, v35
	v_cvt_pk_bf16_f32 v44, v49, v52
	v_cvt_pk_bf16_f32 v45, v53, v45
	global_store_dwordx4 v[46:47], v[42:45], off
	v_pk_mul_f32 v[26:27], v[26:27], v[158:159] op_sel_hi:[1,0]
	s_mov_b64 s[10:11], 0x240000
	v_mul_f32_e32 v42, v34, v34
	v_max_f32_e32 v34, 0, v36
	v_mul_f32_e32 v0, v0, v0
	v_mul_f32_e32 v43, v34, v34
	v_max_f32_e32 v34, 0, v37
	v_pk_mul_f32 v[32:33], v[32:33], v[158:159] op_sel_hi:[1,0]
	v_pk_mul_f32 v[30:31], v[30:31], v[158:159] op_sel_hi:[1,0]
	v_max_f32_e32 v26, 0, v26
	v_lshl_add_u64 v[50:51], v[164:165], 0, s[10:11]
	v_mul_f32_e32 v38, v38, v38
	v_mul_f32_e32 v39, v39, v39
	v_mul_f32_e32 v40, v40, v40
	v_mul_f32_e32 v37, v34, v34
	v_cvt_pk_bf16_f32 v34, v0, v38
	v_cvt_pk_bf16_f32 v35, v39, v40
	v_cvt_pk_bf16_f32 v36, v41, v42
	v_pk_mul_f32 v[28:29], v[28:29], v[158:159] op_sel_hi:[1,0]
	v_max_f32_e32 v0, 0, v30
	v_max_f32_e32 v30, 0, v31
	v_max_f32_e32 v31, 0, v32
	v_max_f32_e32 v32, 0, v33
	v_mul_f32_e32 v33, v26, v26
	v_max_f32_e32 v26, 0, v27
	v_cvt_pk_bf16_f32 v37, v43, v37
	global_store_dwordx4 v[50:51], v[34:37], off offset:256
	v_mul_f32_e32 v30, v30, v30
	s_mov_b32 s7, 0x280000
	v_mul_f32_e32 v36, v26, v26
	v_max_f32_e32 v26, 0, v28
	v_mul_f32_e32 v37, v26, v26
	v_max_f32_e32 v26, 0, v29
	v_pk_mul_f32 v[18:19], v[18:19], v[158:159] op_sel_hi:[1,0]
	v_mul_f32_e32 v0, v0, v0
	v_mul_f32_e32 v31, v31, v31
	v_mul_f32_e32 v29, v26, v26
	v_cvt_pk_bf16_f32 v26, v0, v30
	v_add_co_u32_e32 v30, vcc, s7, v164
	v_pk_mul_f32 v[24:25], v[24:25], v[158:159] op_sel_hi:[1,0]
	v_pk_mul_f32 v[22:23], v[22:23], v[158:159] op_sel_hi:[1,0]
	v_max_f32_e32 v18, 0, v18
	v_mul_f32_e32 v32, v32, v32
	v_cvt_pk_bf16_f32 v27, v31, v32
	v_addc_co_u32_e32 v31, vcc, 0, v165, vcc
	v_pk_mul_f32 v[20:21], v[20:21], v[158:159] op_sel_hi:[1,0]
	v_max_f32_e32 v0, 0, v22
	v_max_f32_e32 v22, 0, v23
	v_max_f32_e32 v23, 0, v24
	v_max_f32_e32 v24, 0, v25
	v_mul_f32_e32 v25, v18, v18
	v_max_f32_e32 v18, 0, v19
	v_cvt_pk_bf16_f32 v28, v33, v36
	v_cvt_pk_bf16_f32 v29, v37, v29
	global_store_dwordx4 v[30:31], v[26:29], off
	v_pk_mul_f32 v[10:11], v[10:11], v[162:163] op_sel_hi:[1,0]
	s_mov_b64 s[10:11], 0x280000
	v_mul_f32_e32 v26, v18, v18
	v_max_f32_e32 v18, 0, v20
	v_mul_f32_e32 v0, v0, v0
	v_mul_f32_e32 v27, v18, v18
	v_max_f32_e32 v18, 0, v21
	v_pk_mul_f32 v[16:17], v[16:17], v[162:163] op_sel_hi:[1,0]
	v_pk_mul_f32 v[14:15], v[14:15], v[162:163] op_sel_hi:[1,0]
	v_max_f32_e32 v10, 0, v10
	v_lshl_add_u64 v[34:35], v[164:165], 0, s[10:11]
	v_mul_f32_e32 v22, v22, v22
	v_mul_f32_e32 v23, v23, v23
	v_mul_f32_e32 v24, v24, v24
	v_mul_f32_e32 v21, v18, v18
	v_cvt_pk_bf16_f32 v18, v0, v22
	v_cvt_pk_bf16_f32 v19, v23, v24
	v_cvt_pk_bf16_f32 v20, v25, v26
	v_pk_mul_f32 v[12:13], v[12:13], v[162:163] op_sel_hi:[1,0]
	v_max_f32_e32 v0, 0, v14
	v_max_f32_e32 v14, 0, v15
	v_max_f32_e32 v15, 0, v16
	v_max_f32_e32 v16, 0, v17
	v_mul_f32_e32 v17, v10, v10
	v_max_f32_e32 v10, 0, v11
	v_cvt_pk_bf16_f32 v21, v27, v21
	global_store_dwordx4 v[34:35], v[18:21], off offset:256
	v_mul_f32_e32 v0, v0, v0
	v_mul_f32_e32 v14, v14, v14
	v_mul_f32_e32 v20, v10, v10
	v_max_f32_e32 v10, 0, v12
	v_mul_f32_e32 v21, v10, v10
	v_max_f32_e32 v10, 0, v13
	s_mov_b32 s7, 0x2c0000
	v_pk_mul_f32 v[4:5], v[4:5], v[162:163] op_sel_hi:[1,0]
	v_pk_mul_f32 v[2:3], v[2:3], v[162:163] op_sel_hi:[1,0]
	v_pk_mul_f32 v[6:7], v[6:7], v[162:163] op_sel_hi:[1,0]
	v_mul_f32_e32 v15, v15, v15
	v_mul_f32_e32 v13, v10, v10
	v_cvt_pk_bf16_f32 v10, v0, v14
	v_add_co_u32_e32 v14, vcc, s7, v164
	v_pk_mul_f32 v[8:9], v[8:9], v[162:163] op_sel_hi:[1,0]
	v_max_f32_e32 v0, 0, v2
	v_max_f32_e32 v2, 0, v3
	v_max_f32_e32 v3, 0, v4
	v_max_f32_e32 v4, 0, v5
	v_max_f32_e32 v5, 0, v6
	s_mov_b64 s[10:11], 0x2c0000
	v_mul_f32_e32 v16, v16, v16
	v_cvt_pk_bf16_f32 v11, v15, v16
	v_addc_co_u32_e32 v15, vcc, 0, v165, vcc
	v_mul_f32_e32 v2, v2, v2
	v_mul_f32_e32 v3, v3, v3
	v_mul_f32_e32 v4, v4, v4
	v_mul_f32_e32 v5, v5, v5
	v_max_f32_e32 v6, 0, v7
	v_max_f32_e32 v7, 0, v8
	v_max_f32_e32 v8, 0, v9
	v_lshl_add_u64 v[18:19], v[164:165], 0, s[10:11]
	v_cvt_pk_bf16_f32 v12, v17, v20
	v_cvt_pk_bf16_f32 v13, v21, v13
	global_store_dwordx4 v[14:15], v[10:13], off
	v_mul_f32_e32 v0, v0, v0
	v_mul_f32_e32 v6, v6, v6
	v_mul_f32_e32 v7, v7, v7
	v_mul_f32_e32 v8, v8, v8
	v_cvt_pk_bf16_f32 v2, v0, v2
	v_cvt_pk_bf16_f32 v3, v3, v4
	v_cvt_pk_bf16_f32 v4, v5, v6
	v_cvt_pk_bf16_f32 v5, v7, v8
	s_mov_b64 s[10:11], -1
	s_andn2_b64 vcc, exec, s[4:5]
	global_store_dwordx4 v[18:19], v[2:5], off offset:256
	s_cbranch_vccnz .LBB0_1160
	s_andn2_b64 vcc, exec, s[0:1]
	s_cbranch_vccnz .LBB0_1159
	s_barrier
	s_branch .LBB0_1159

.LBB0_1237:
	v_lshl_or_b32 v218, s12, 8, v252
	v_lshl_add_u32 v234, s14, 8, v250
	v_ashrrev_i32_e32 v219, 31, v218
	v_lshlrev_b64 v[236:237], 1, v[218:219]
	v_ashrrev_i32_e32 v235, 31, v234
	v_lshl_add_u64 v[138:139], v[200:201], 0, v[236:237]
	v_lshlrev_b64 v[238:239], 12, v[234:235]
	v_lshl_add_u64 v[134:135], v[138:139], 0, v[238:239]
	global_load_dwordx4 v[194:197], v[134:135], off
	global_load_dwordx4 v[190:193], v[134:135], off offset:256
	v_or_b32_e32 v232, 16, v234
	v_ashrrev_i32_e32 v233, 31, v232
	v_lshlrev_b64 v[134:135], 12, v[232:233]
	v_or_b32_e32 v230, 32, v234
	v_lshl_add_u64 v[134:135], v[138:139], 0, v[134:135]
	v_ashrrev_i32_e32 v231, 31, v230
	global_load_dwordx4 v[186:189], v[134:135], off
	global_load_dwordx4 v[182:185], v[134:135], off offset:256
	v_lshlrev_b64 v[134:135], 12, v[230:231]
	v_or_b32_e32 v228, 48, v234
	v_lshl_add_u64 v[134:135], v[138:139], 0, v[134:135]
	v_ashrrev_i32_e32 v229, 31, v228
	global_load_dwordx4 v[178:181], v[134:135], off
	global_load_dwordx4 v[174:177], v[134:135], off offset:256
	v_lshlrev_b64 v[134:135], 12, v[228:229]
	v_add_u32_e32 v226, 0x80, v234
	v_lshl_add_u64 v[134:135], v[138:139], 0, v[134:135]
	v_ashrrev_i32_e32 v227, 31, v226
	global_load_dwordx4 v[170:173], v[134:135], off
	global_load_dwordx4 v[166:169], v[134:135], off offset:256
	v_lshlrev_b64 v[134:135], 12, v[226:227]
	v_add_u32_e32 v224, 0x90, v234
	v_lshl_add_u64 v[134:135], v[138:139], 0, v[134:135]
	v_ashrrev_i32_e32 v225, 31, v224
	global_load_dwordx4 v[162:165], v[134:135], off
	global_load_dwordx4 v[158:161], v[134:135], off offset:256
	v_lshlrev_b64 v[134:135], 12, v[224:225]
	v_add_u32_e32 v222, 0xa0, v234
	v_add_u32_e32 v220, 0xb0, v234
	v_lshl_add_u64 v[134:135], v[138:139], 0, v[134:135]
	v_ashrrev_i32_e32 v223, 31, v222
	v_ashrrev_i32_e32 v221, 31, v220
	global_load_dwordx4 v[154:157], v[134:135], off
	global_load_dwordx4 v[150:153], v[134:135], off offset:256
	v_lshlrev_b64 v[134:135], 12, v[222:223]
	v_lshlrev_b64 v[140:141], 12, v[220:221]
	v_lshl_add_u64 v[134:135], v[138:139], 0, v[134:135]
	v_lshl_add_u64 v[138:139], v[138:139], 0, v[140:141]
	global_load_dwordx4 v[142:145], v[134:135], off
	s_nop 0
	global_load_dwordx4 v[134:137], v[134:135], off offset:256
	s_nop 0
	global_load_dwordx4 v[146:149], v[138:139], off
	s_nop 0
	global_load_dwordx4 v[138:141], v[138:139], off offset:256
	s_mov_b64 vcc, s[2:3]
	s_cbranch_vccz .Lalign_skip_5
	s_barrier
.Lalign_skip_5:
	s_lshl_b32 s12, s12, 2
	s_ashr_i32 s13, s12, 31
	s_waitcnt vmcnt(0)
	v_lshlrev_b32_e32 v206, 16, v194
	v_and_b32_e32 v207, 0xffff0000, v194
	v_lshlrev_b32_e32 v194, 16, v195
	v_and_b32_e32 v195, 0xffff0000, v195
	v_pk_add_f32 v[128:129], v[128:129], v[194:195]
	v_pk_add_f32 v[126:127], v[126:127], v[206:207]
	v_lshlrev_b32_e32 v208, 16, v196
	v_and_b32_e32 v209, 0xffff0000, v196
	v_mul_f32_e32 v0, v127, v127
	v_mul_f32_e32 v194, v129, v129
	v_pk_add_f32 v[130:131], v[130:131], v[208:209]
	v_fmac_f32_e32 v0, v126, v126
	v_fmac_f32_e32 v194, v128, v128
	v_add_f32_e32 v0, v0, v194
	v_mul_f32_e32 v194, v131, v131
	v_lshlrev_b32_e32 v196, 16, v197
	v_and_b32_e32 v197, 0xffff0000, v197
	v_fmac_f32_e32 v194, v130, v130
	v_cvt_pk_bf16_f32 v126, v126, v127
	v_cvt_pk_bf16_f32 v127, v128, v129
	v_cvt_pk_bf16_f32 v128, v130, v131
	v_lshl_add_u64 v[130:131], v[200:201], 0, v[238:239]
	v_pk_add_f32 v[132:133], v[132:133], v[196:197]
	v_lshl_add_u64 v[130:131], v[130:131], 0, v[236:237]
	v_cvt_pk_bf16_f32 v129, v132, v133
	v_mul_f32_e32 v195, v133, v133
	global_store_dwordx4 v[130:131], v[126:129], off
	v_fmac_f32_e32 v195, v132, v132
	v_lshlrev_b32_e32 v132, 16, v192
	v_lshlrev_b32_e32 v126, 16, v190
	v_and_b32_e32 v127, 0xffff0000, v190
	v_lshlrev_b32_e32 v128, 16, v191
	v_and_b32_e32 v129, 0xffff0000, v191
	v_and_b32_e32 v133, 0xffff0000, v192
	v_lshlrev_b32_e32 v190, 16, v193
	v_and_b32_e32 v191, 0xffff0000, v193
	v_pk_add_f32 v[124:125], v[124:125], v[128:129]
	v_pk_add_f32 v[122:123], v[122:123], v[126:127]
	v_pk_add_f32 v[126:127], v[120:121], v[190:191]
	v_pk_add_f32 v[120:121], v[118:119], v[132:133]
	v_mul_f32_e32 v118, v123, v123
	v_mul_f32_e32 v119, v125, v125
	v_fmac_f32_e32 v118, v122, v122
	v_fmac_f32_e32 v119, v124, v124
	v_add_f32_e32 v118, v118, v119
	v_mul_f32_e32 v119, v121, v121
	v_mul_f32_e32 v128, v127, v127
	v_fmac_f32_e32 v119, v120, v120
	v_fmac_f32_e32 v128, v126, v126
	v_add_f32_e32 v194, v194, v195
	v_add_f32_e32 v119, v119, v128
	v_add_f32_e32 v0, v0, v194
	v_add_f32_e32 v118, v118, v119
	v_add_f32_e32 v0, v0, v118
	v_cvt_pk_bf16_f32 v118, v122, v123
	v_cvt_pk_bf16_f32 v119, v124, v125
	v_cvt_pk_bf16_f32 v120, v120, v121
	v_cvt_pk_bf16_f32 v121, v126, v127
	global_store_dwordx4 v[130:131], v[118:121], off offset:256
	s_nop 1
	v_mov_b32_e32 v118, v0
	s_nop 1
	v_permlane16_swap_b32_e32 v0, v118
	v_add_f32_e32 v0, v0, v118
	v_mov_b32_e32 v118, v0
	s_nop 1
	v_permlane32_swap_b32_e32 v0, v118
	s_and_saveexec_b64 s[14:15], s[4:5]
	s_cbranch_execz .LBB0_1239
	v_lshlrev_b64 v[120:121], 6, v[234:235]
	v_lshl_add_u64 v[120:121], v[4:5], 0, v[120:121]
	v_lshl_add_u64 v[120:121], s[12:13], 1, v[120:121]
	s_lshl_b32 s16, s27, 1
	s_mov_b32 s17, s40
	v_lshl_add_u64 v[120:121], v[120:121], 0, s[16:17]
	v_add_f32_e32 v0, v0, v118
	v_cvt_pk_bf16_f32 v0, v0, v1
	global_store_short v[120:121], v0, off

.LBB0_1271:
	v_lshl_add_u32 v228, s10, 8, v230
	v_lshl_or_b32 v226, s11, 8, v232
	v_ashrrev_i32_e32 v227, 31, v226
	v_ashrrev_i32_e32 v229, 31, v228
	v_lshl_add_u64 v[132:133], v[226:227], 1, v[200:201]
	v_lshlrev_b64 v[134:135], 12, v[228:229]
	v_lshl_add_u64 v[134:135], v[132:133], 0, v[134:135]
	global_load_dwordx4 v[234:237], v[134:135], off
	global_load_dwordx4 v[188:191], v[134:135], off offset:256
	v_or_b32_e32 v224, 16, v228
	v_ashrrev_i32_e32 v225, 31, v224
	v_lshlrev_b64 v[134:135], 12, v[224:225]
	v_lshl_add_u64 v[134:135], v[132:133], 0, v[134:135]
	global_load_dwordx4 v[184:187], v[134:135], off
	global_load_dwordx4 v[180:183], v[134:135], off offset:256
	v_or_b32_e32 v222, 32, v228
	v_ashrrev_i32_e32 v223, 31, v222
	v_lshlrev_b64 v[134:135], 12, v[222:223]
	v_lshl_add_u64 v[134:135], v[132:133], 0, v[134:135]
	global_load_dwordx4 v[176:179], v[134:135], off
	global_load_dwordx4 v[172:175], v[134:135], off offset:256
	v_or_b32_e32 v220, 48, v228
	v_ashrrev_i32_e32 v221, 31, v220
	v_lshlrev_b64 v[134:135], 12, v[220:221]
	v_lshl_add_u64 v[134:135], v[132:133], 0, v[134:135]
	global_load_dwordx4 v[168:171], v[134:135], off
	global_load_dwordx4 v[164:167], v[134:135], off offset:256
	v_add_u32_e32 v218, 0x80, v228
	v_ashrrev_i32_e32 v219, 31, v218
	v_lshlrev_b64 v[134:135], 12, v[218:219]
	v_lshl_add_u64 v[134:135], v[132:133], 0, v[134:135]
	global_load_dwordx4 v[160:163], v[134:135], off
	global_load_dwordx4 v[156:159], v[134:135], off offset:256
	v_add_u32_e32 v216, 0x90, v228
	v_ashrrev_i32_e32 v217, 31, v216
	v_lshlrev_b64 v[134:135], 12, v[216:217]
	v_lshl_add_u64 v[134:135], v[132:133], 0, v[134:135]
	global_load_dwordx4 v[152:155], v[134:135], off
	global_load_dwordx4 v[148:151], v[134:135], off offset:256
	v_add_u32_e32 v214, 0xa0, v228
	v_ashrrev_i32_e32 v215, 31, v214
	v_lshlrev_b64 v[134:135], 12, v[214:215]
	v_lshl_add_u64 v[134:135], v[132:133], 0, v[134:135]
	global_load_dwordx4 v[144:147], v[134:135], off
	global_load_dwordx4 v[136:139], v[134:135], off offset:256
	v_add_u32_e32 v212, 0xb0, v228
	v_ashrrev_i32_e32 v213, 31, v212
	v_lshlrev_b64 v[134:135], 12, v[212:213]
	v_lshl_add_u64 v[132:133], v[132:133], 0, v[134:135]
	global_load_dwordx4 v[140:143], v[132:133], off
	s_nop 0
	global_load_dwordx4 v[132:135], v[132:133], off offset:256
	s_mov_b64 vcc, s[2:3]
	s_cbranch_vccz .Lalign_skip_6
	s_barrier
.Lalign_skip_6:
	s_mov_b64 s[10:11], -1
	s_andn2_b64 vcc, exec, s[4:5]
	s_waitcnt vmcnt(0)
	v_lshlrev_b32_e32 v206, 16, v234
	v_and_b32_e32 v207, 0xffff0000, v234
	v_lshlrev_b32_e32 v208, 16, v235
	v_and_b32_e32 v209, 0xffff0000, v235
	v_pk_add_f32 v[234:235], v[124:125], v[206:207]
	v_lshlrev_b64 v[124:125], 13, v[228:229]
	v_lshlrev_b32_e32 v238, 16, v236
	v_and_b32_e32 v239, 0xffff0000, v236
	v_lshlrev_b32_e32 v250, 16, v237
	v_and_b32_e32 v251, 0xffff0000, v237
	v_pk_add_f32 v[236:237], v[126:127], v[208:209]
	v_lshl_add_u64 v[126:127], v[2:3], 0, v[124:125]
	v_lshlrev_b64 v[124:125], 2, v[226:227]
	v_pk_add_f32 v[130:131], v[130:131], v[250:251]
	v_pk_add_f32 v[128:129], v[128:129], v[238:239]
	v_lshl_add_u64 v[126:127], v[126:127], 0, v[124:125]
	global_store_dwordx4 v[126:127], v[234:237], off
	global_store_dwordx4 v[126:127], v[128:131], off offset:16
	s_nop 1
	v_lshlrev_b32_e32 v128, 16, v188
	v_and_b32_e32 v129, 0xffff0000, v188
	v_lshlrev_b32_e32 v130, 16, v189
	v_and_b32_e32 v131, 0xffff0000, v189
	v_lshlrev_b32_e32 v188, 16, v190
	v_and_b32_e32 v189, 0xffff0000, v190
	v_lshlrev_b32_e32 v190, 16, v191
	v_and_b32_e32 v191, 0xffff0000, v191
	v_pk_add_f32 v[122:123], v[122:123], v[130:131]
	v_pk_add_f32 v[120:121], v[120:121], v[128:129]
	v_pk_add_f32 v[116:117], v[116:117], v[188:189]
	v_pk_add_f32 v[118:119], v[118:119], v[190:191]
	global_store_dwordx4 v[126:127], v[120:123], off offset:512
	global_store_dwordx4 v[126:127], v[116:119], off offset:528
	s_nop 0
	v_lshlrev_b32_e32 v120, 16, v186
	v_lshlrev_b32_e32 v116, 16, v184
	v_and_b32_e32 v117, 0xffff0000, v184
	v_pk_add_f32 v[112:113], v[112:113], v[116:117]
	v_lshlrev_b64 v[116:117], 13, v[224:225]
	v_lshlrev_b32_e32 v118, 16, v185
	v_and_b32_e32 v119, 0xffff0000, v185
	v_and_b32_e32 v121, 0xffff0000, v186
	v_lshlrev_b32_e32 v122, 16, v187
	v_and_b32_e32 v123, 0xffff0000, v187
	v_lshl_add_u64 v[116:117], v[2:3], 0, v[116:117]
	v_pk_add_f32 v[114:115], v[114:115], v[118:119]
	v_pk_add_f32 v[110:111], v[110:111], v[122:123]
	v_pk_add_f32 v[108:109], v[108:109], v[120:121]
	v_lshl_add_u64 v[116:117], v[116:117], 0, v[124:125]
	global_store_dwordx4 v[116:117], v[112:115], off
	global_store_dwordx4 v[116:117], v[108:111], off offset:16
	s_nop 0
	v_lshlrev_b32_e32 v112, 16, v182
	v_lshlrev_b32_e32 v108, 16, v180
	v_and_b32_e32 v109, 0xffff0000, v180
	v_lshlrev_b32_e32 v110, 16, v181
	v_and_b32_e32 v111, 0xffff0000, v181
	v_and_b32_e32 v113, 0xffff0000, v182
	v_lshlrev_b32_e32 v114, 16, v183
	v_and_b32_e32 v115, 0xffff0000, v183
	v_pk_add_f32 v[106:107], v[106:107], v[110:111]
	v_pk_add_f32 v[104:105], v[104:105], v[108:109]
	v_pk_add_f32 v[100:101], v[100:101], v[112:113]
	v_pk_add_f32 v[102:103], v[102:103], v[114:115]
	global_store_dwordx4 v[116:117], v[104:107], off offset:512
	global_store_dwordx4 v[116:117], v[100:103], off offset:528
	s_nop 0
	v_lshlrev_b32_e32 v104, 16, v178
	v_lshlrev_b32_e32 v100, 16, v176
	v_and_b32_e32 v101, 0xffff0000, v176
	v_pk_add_f32 v[96:97], v[96:97], v[100:101]
	v_lshlrev_b64 v[100:101], 13, v[222:223]
	v_lshlrev_b32_e32 v102, 16, v177
	v_and_b32_e32 v103, 0xffff0000, v177
	v_and_b32_e32 v105, 0xffff0000, v178
	v_lshlrev_b32_e32 v106, 16, v179
	v_and_b32_e32 v107, 0xffff0000, v179
	v_lshl_add_u64 v[100:101], v[2:3], 0, v[100:101]
	v_pk_add_f32 v[98:99], v[98:99], v[102:103]
	v_pk_add_f32 v[94:95], v[94:95], v[106:107]
	v_pk_add_f32 v[92:93], v[92:93], v[104:105]
	v_lshl_add_u64 v[100:101], v[100:101], 0, v[124:125]
	global_store_dwordx4 v[100:101], v[96:99], off
	global_store_dwordx4 v[100:101], v[92:95], off offset:16
	s_nop 0
	v_lshlrev_b32_e32 v96, 16, v174
	v_lshlrev_b32_e32 v92, 16, v172
	v_and_b32_e32 v93, 0xffff0000, v172
	v_lshlrev_b32_e32 v94, 16, v173
	v_and_b32_e32 v95, 0xffff0000, v173
	v_and_b32_e32 v97, 0xffff0000, v174
	v_lshlrev_b32_e32 v98, 16, v175
	v_and_b32_e32 v99, 0xffff0000, v175
	v_pk_add_f32 v[90:91], v[90:91], v[94:95]
	v_pk_add_f32 v[88:89], v[88:89], v[92:93]
	v_pk_add_f32 v[84:85], v[84:85], v[96:97]
	v_pk_add_f32 v[86:87], v[86:87], v[98:99]
	global_store_dwordx4 v[100:101], v[88:91], off offset:512
	global_store_dwordx4 v[100:101], v[84:87], off offset:528
	s_nop 0
	v_lshlrev_b32_e32 v88, 16, v170
	v_lshlrev_b32_e32 v84, 16, v168
	v_and_b32_e32 v85, 0xffff0000, v168
	v_pk_add_f32 v[80:81], v[80:81], v[84:85]
	v_lshlrev_b64 v[84:85], 13, v[220:221]
	v_lshlrev_b32_e32 v86, 16, v169
	v_and_b32_e32 v87, 0xffff0000, v169
	v_and_b32_e32 v89, 0xffff0000, v170
	v_lshlrev_b32_e32 v90, 16, v171
	v_and_b32_e32 v91, 0xffff0000, v171
	v_lshl_add_u64 v[84:85], v[2:3], 0, v[84:85]
	v_pk_add_f32 v[82:83], v[82:83], v[86:87]
	v_pk_add_f32 v[78:79], v[78:79], v[90:91]
	v_pk_add_f32 v[76:77], v[76:77], v[88:89]
	v_lshl_add_u64 v[84:85], v[84:85], 0, v[124:125]
	global_store_dwordx4 v[84:85], v[80:83], off
	global_store_dwordx4 v[84:85], v[76:79], off offset:16
	s_nop 0
	v_lshlrev_b32_e32 v80, 16, v166
	v_lshlrev_b32_e32 v76, 16, v164
	v_and_b32_e32 v77, 0xffff0000, v164
	v_lshlrev_b32_e32 v78, 16, v165
	v_and_b32_e32 v79, 0xffff0000, v165
	v_and_b32_e32 v81, 0xffff0000, v166
	v_lshlrev_b32_e32 v82, 16, v167
	v_and_b32_e32 v83, 0xffff0000, v167
	v_pk_add_f32 v[74:75], v[74:75], v[78:79]
	v_pk_add_f32 v[72:73], v[72:73], v[76:77]
	v_pk_add_f32 v[68:69], v[68:69], v[80:81]
	v_pk_add_f32 v[70:71], v[70:71], v[82:83]
	global_store_dwordx4 v[84:85], v[72:75], off offset:512
	global_store_dwordx4 v[84:85], v[68:71], off offset:528
	s_nop 0
	v_lshlrev_b32_e32 v72, 16, v162
	v_lshlrev_b32_e32 v68, 16, v160
	v_and_b32_e32 v69, 0xffff0000, v160
	v_pk_add_f32 v[64:65], v[64:65], v[68:69]
	v_lshlrev_b64 v[68:69], 13, v[218:219]
	v_lshlrev_b32_e32 v70, 16, v161
	v_and_b32_e32 v71, 0xffff0000, v161
	v_and_b32_e32 v73, 0xffff0000, v162
	v_lshlrev_b32_e32 v74, 16, v163
	v_and_b32_e32 v75, 0xffff0000, v163
	v_lshl_add_u64 v[68:69], v[2:3], 0, v[68:69]
	v_pk_add_f32 v[66:67], v[66:67], v[70:71]
	v_pk_add_f32 v[62:63], v[62:63], v[74:75]
	v_pk_add_f32 v[60:61], v[60:61], v[72:73]
	v_lshl_add_u64 v[68:69], v[68:69], 0, v[124:125]
	global_store_dwordx4 v[68:69], v[64:67], off
	global_store_dwordx4 v[68:69], v[60:63], off offset:16
	s_nop 0
	v_lshlrev_b32_e32 v64, 16, v158
	v_lshlrev_b32_e32 v60, 16, v156
	v_and_b32_e32 v61, 0xffff0000, v156
	v_lshlrev_b32_e32 v62, 16, v157
	v_and_b32_e32 v63, 0xffff0000, v157
	v_and_b32_e32 v65, 0xffff0000, v158
	v_lshlrev_b32_e32 v66, 16, v159
	v_and_b32_e32 v67, 0xffff0000, v159
	v_pk_add_f32 v[58:59], v[58:59], v[62:63]
	v_pk_add_f32 v[56:57], v[56:57], v[60:61]
	v_pk_add_f32 v[52:53], v[52:53], v[64:65]
	v_pk_add_f32 v[54:55], v[54:55], v[66:67]
	global_store_dwordx4 v[68:69], v[56:59], off offset:512
	global_store_dwordx4 v[68:69], v[52:55], off offset:528
	s_nop 0
	v_lshlrev_b32_e32 v56, 16, v154
	v_lshlrev_b32_e32 v52, 16, v152
	v_and_b32_e32 v53, 0xffff0000, v152
	v_pk_add_f32 v[48:49], v[48:49], v[52:53]
	v_lshlrev_b64 v[52:53], 13, v[216:217]
	v_lshlrev_b32_e32 v54, 16, v153
	v_and_b32_e32 v55, 0xffff0000, v153
	v_and_b32_e32 v57, 0xffff0000, v154
	v_lshlrev_b32_e32 v58, 16, v155
	v_and_b32_e32 v59, 0xffff0000, v155
	v_lshl_add_u64 v[52:53], v[2:3], 0, v[52:53]
	v_pk_add_f32 v[50:51], v[50:51], v[54:55]
	v_pk_add_f32 v[46:47], v[46:47], v[58:59]
	v_pk_add_f32 v[44:45], v[44:45], v[56:57]
	v_lshl_add_u64 v[52:53], v[52:53], 0, v[124:125]
	global_store_dwordx4 v[52:53], v[48:51], off
	global_store_dwordx4 v[52:53], v[44:47], off offset:16
	s_nop 0
	v_lshlrev_b32_e32 v48, 16, v150
	v_lshlrev_b32_e32 v44, 16, v148
	v_and_b32_e32 v45, 0xffff0000, v148
	v_lshlrev_b32_e32 v46, 16, v149
	v_and_b32_e32 v47, 0xffff0000, v149
	v_and_b32_e32 v49, 0xffff0000, v150
	v_lshlrev_b32_e32 v50, 16, v151
	v_and_b32_e32 v51, 0xffff0000, v151
	v_pk_add_f32 v[42:43], v[42:43], v[46:47]
	v_pk_add_f32 v[40:41], v[40:41], v[44:45]
	v_pk_add_f32 v[36:37], v[36:37], v[48:49]
	v_pk_add_f32 v[38:39], v[38:39], v[50:51]
	global_store_dwordx4 v[52:53], v[40:43], off offset:512
	global_store_dwordx4 v[52:53], v[36:39], off offset:528
	s_nop 0
	v_lshlrev_b32_e32 v40, 16, v146
	v_lshlrev_b32_e32 v36, 16, v144
	v_and_b32_e32 v37, 0xffff0000, v144
	v_pk_add_f32 v[32:33], v[32:33], v[36:37]
	v_lshlrev_b64 v[36:37], 13, v[214:215]
	v_lshlrev_b32_e32 v38, 16, v145
	v_and_b32_e32 v39, 0xffff0000, v145
	v_and_b32_e32 v41, 0xffff0000, v146
	v_lshlrev_b32_e32 v42, 16, v147
	v_and_b32_e32 v43, 0xffff0000, v147
	v_lshl_add_u64 v[36:37], v[2:3], 0, v[36:37]
	v_pk_add_f32 v[34:35], v[34:35], v[38:39]
	v_pk_add_f32 v[30:31], v[30:31], v[42:43]
	v_pk_add_f32 v[28:29], v[28:29], v[40:41]
	v_lshl_add_u64 v[36:37], v[36:37], 0, v[124:125]
	global_store_dwordx4 v[36:37], v[32:35], off
	global_store_dwordx4 v[36:37], v[28:31], off offset:16
	s_nop 0
	v_lshlrev_b32_e32 v32, 16, v138
	v_lshlrev_b32_e32 v28, 16, v136
	v_and_b32_e32 v29, 0xffff0000, v136
	v_lshlrev_b32_e32 v30, 16, v137
	v_and_b32_e32 v31, 0xffff0000, v137
	v_and_b32_e32 v33, 0xffff0000, v138
	v_lshlrev_b32_e32 v34, 16, v139
	v_and_b32_e32 v35, 0xffff0000, v139
	v_pk_add_f32 v[26:27], v[26:27], v[30:31]
	v_pk_add_f32 v[24:25], v[24:25], v[28:29]
	v_pk_add_f32 v[20:21], v[20:21], v[32:33]
	v_pk_add_f32 v[22:23], v[22:23], v[34:35]
	global_store_dwordx4 v[36:37], v[24:27], off offset:512
	global_store_dwordx4 v[36:37], v[20:23], off offset:528
	s_nop 0
	v_lshlrev_b32_e32 v24, 16, v142
	v_lshlrev_b32_e32 v20, 16, v140
	v_and_b32_e32 v21, 0xffff0000, v140
	v_pk_add_f32 v[16:17], v[16:17], v[20:21]
	v_lshlrev_b64 v[20:21], 13, v[212:213]
	v_lshlrev_b32_e32 v22, 16, v141
	v_and_b32_e32 v23, 0xffff0000, v141
	v_and_b32_e32 v25, 0xffff0000, v142
	v_lshlrev_b32_e32 v26, 16, v143
	v_and_b32_e32 v27, 0xffff0000, v143
	v_lshl_add_u64 v[20:21], v[2:3], 0, v[20:21]
	v_pk_add_f32 v[18:19], v[18:19], v[22:23]
	v_pk_add_f32 v[14:15], v[14:15], v[26:27]
	v_pk_add_f32 v[12:13], v[12:13], v[24:25]
	v_lshl_add_u64 v[20:21], v[20:21], 0, v[124:125]
	global_store_dwordx4 v[20:21], v[16:19], off
	global_store_dwordx4 v[20:21], v[12:15], off offset:16
	s_nop 0
	v_lshlrev_b32_e32 v16, 16, v134
	v_lshlrev_b32_e32 v12, 16, v132
	v_and_b32_e32 v13, 0xffff0000, v132
	v_lshlrev_b32_e32 v14, 16, v133
	v_and_b32_e32 v15, 0xffff0000, v133
	v_and_b32_e32 v17, 0xffff0000, v134
	v_lshlrev_b32_e32 v18, 16, v135
	v_and_b32_e32 v19, 0xffff0000, v135
	v_pk_add_f32 v[10:11], v[10:11], v[14:15]
	v_pk_add_f32 v[8:9], v[8:9], v[12:13]
	v_pk_add_f32 v[6:7], v[6:7], v[18:19]
	v_pk_add_f32 v[4:5], v[4:5], v[16:17]
	global_store_dwordx4 v[20:21], v[8:11], off offset:512
	global_store_dwordx4 v[20:21], v[4:7], off offset:528
	s_cbranch_vccnz .LBB0_1264
	s_andn2_b64 vcc, exec, s[0:1]
	s_cbranch_vccnz .LBB0_1263
	s_barrier
	s_branch .LBB0_1263
